# PV3: pair-tile GEMM with LDS-DMA pieces staggered per wave (4 loop variants, at most 2 pieces per MFMA slot per block); dead original epilogue code deleted
# speedup vs baseline: 1.0292x; 1.0032x over previous
.LBB0_171:
	s_mul_i32 s86, s2, 0x3e0000
	s_lshl_b64 s[0:1], s[86:87], 1
	v_readlane_b32 s3, v234, 40
	s_add_u32 s22, s3, s0
	v_readlane_b32 s0, v234, 41
	s_addc_u32 s23, s0, s1
	s_lshl_b32 s86, s2, 2
	s_mov_b32 s3, s87
	s_mov_b32 s24, s87
	s_branch .LBB0_175
.LBB0_173:
	s_or_b64 exec, exec, s[6:7]
	s_bitcmp1_b32 s0, 0
	s_cbranch_scc1 .Lpv_done
	s_add_i32 s0, s0, 1
	v_mov_b32_e32 v18, v104
	v_mov_b32_e32 v19, v105
	v_mov_b32_e32 v20, v106
	v_mov_b32_e32 v21, v107
	v_mov_b32_e32 v22, v108
	v_mov_b32_e32 v23, v109
	v_mov_b32_e32 v24, v110
	v_mov_b32_e32 v25, v111
	v_mov_b32_e32 v26, v112
	v_mov_b32_e32 v27, v113
	v_mov_b32_e32 v28, v114
	v_mov_b32_e32 v29, v115
	v_mov_b32_e32 v30, v116
	v_mov_b32_e32 v31, v117
	v_mov_b32_e32 v32, v118
	v_mov_b32_e32 v33, v119
	v_mov_b32_e32 v50, v128
	v_mov_b32_e32 v51, v129
	v_mov_b32_e32 v52, v130
	v_mov_b32_e32 v53, v131
	v_mov_b32_e32 v54, v132
	v_mov_b32_e32 v55, v133
	v_mov_b32_e32 v56, v134
	v_mov_b32_e32 v57, v135
	v_mov_b32_e32 v58, v136
	v_mov_b32_e32 v59, v137
	v_mov_b32_e32 v60, v138
	v_mov_b32_e32 v61, v139
	v_mov_b32_e32 v62, v140
	v_mov_b32_e32 v63, v141
	v_mov_b32_e32 v64, v142
	v_mov_b32_e32 v65, v143
	v_mov_b32_e32 v2, v196
	v_mov_b32_e32 v3, v197
	v_mov_b32_e32 v4, v198
	v_mov_b32_e32 v5, v199
	v_mov_b32_e32 v6, v200
	v_mov_b32_e32 v7, v201
	v_mov_b32_e32 v8, v202
	v_mov_b32_e32 v9, v203
	v_mov_b32_e32 v10, v204
	v_mov_b32_e32 v11, v205
	v_mov_b32_e32 v12, v206
	v_mov_b32_e32 v13, v207
	v_mov_b32_e32 v14, v208
	v_mov_b32_e32 v15, v209
	v_mov_b32_e32 v16, v210
	v_mov_b32_e32 v17, v211
	v_mov_b32_e32 v34, v236
	v_mov_b32_e32 v35, v237
	v_mov_b32_e32 v36, v238
	v_mov_b32_e32 v37, v239
	v_mov_b32_e32 v38, v240
	v_mov_b32_e32 v39, v241
	v_mov_b32_e32 v40, v242
	v_mov_b32_e32 v41, v243
	v_mov_b32_e32 v42, v244
	v_mov_b32_e32 v43, v245
	v_mov_b32_e32 v44, v246
	v_mov_b32_e32 v45, v247
	v_mov_b32_e32 v46, v248
	v_mov_b32_e32 v47, v249
	v_mov_b32_e32 v48, v250
	v_mov_b32_e32 v49, v251
	s_branch .LBB0_187

.LBB0_183:
	s_ashr_i32 s1, s0, 31
	s_lshl_b64 s[4:5], s[0:1], 18
	s_add_u32 s8, s48, s4
	s_addc_u32 s9, s49, s5
	s_ashr_i32 s45, s44, 31
	s_lshl_b64 s[6:7], s[44:45], 18
	v_mov_b32_e32 v38, v156
	s_add_u32 s10, s22, s6
	s_addc_u32 s11, s23, s7
	v_readfirstlane_b32 s12, v38
	s_ashr_i32 s1, s12, 6
	v_bfe_u32 v0, v38, 3, 3
	v_lshl_or_b32 v2, s1, 5, v0
	v_min_i32_e32 v4, 0x7f, v2
	v_or_b32_e32 v10, 8, v2
	v_or_b32_e32 v20, 16, v2
	v_or_b32_e32 v28, 24, v2
	v_ashrrev_i32_e32 v5, 31, v4
	v_lshrrev_b32_e32 v11, 1, v10
	v_min_i32_e32 v12, 0x7f, v10
	v_min_i32_e32 v22, 0x7f, v20
	v_min_i32_e32 v30, 0x7f, v28
	v_lshlrev_b64 v[4:5], 11, v[4:5]
	v_lshlrev_b32_e32 v0, 4, v38
	v_and_b32_e32 v40, 48, v38
	v_ashrrev_i32_e32 v3, 31, v2
	v_xor_b32_e32 v11, v11, v38
	v_ashrrev_i32_e32 v13, 31, v12
	v_ashrrev_i32_e32 v23, 31, v22
	v_ashrrev_i32_e32 v31, 31, v30
	v_lshl_add_u64 v[4:5], s[8:9], 0, v[4:5]
	v_and_b32_e32 v41, 0x70, v0
	v_bitop3_b32 v0, v0, v40, s19 bitop3:0x6c
	v_lshlrev_b64 v[6:7], 11, v[2:3]
	v_lshlrev_b64 v[12:13], 11, v[12:13]
	v_lshlrev_b32_e32 v11, 4, v11
	v_lshlrev_b64 v[22:23], 11, v[22:23]
	v_lshrrev_b32_e32 v29, 1, v28
	v_lshlrev_b64 v[30:31], 11, v[30:31]
	s_lshl_b32 s1, s1, 12
	v_lshl_add_u64 v[4:5], v[4:5], 0, v[0:1]
	v_lshl_add_u64 v[8:9], s[10:11], 0, v[6:7]
	v_lshl_add_u64 v[12:13], s[8:9], 0, v[12:13]
	v_and_b32_e32 v14, 0x70, v11
	v_ashrrev_i32_e32 v11, 31, v10
	v_lshl_add_u64 v[22:23], s[8:9], 0, v[22:23]
	v_xor_b32_e32 v29, v29, v38
	v_lshl_add_u64 v[30:31], s[8:9], 0, v[30:31]
	s_add_i32 s8, s1, 0x4000
	s_mov_b32 m0, s1
	v_lshl_add_u64 v[8:9], v[8:9], 0, v[0:1]
	v_mov_b32_e32 v15, v1
	v_lshlrev_b64 v[16:17], 11, v[10:11]
	v_lshlrev_b32_e32 v29, 4, v29
	s_barrier
	global_load_lds_dwordx4 v[4:5], off
	s_mov_b32 m0, s8
	v_lshl_add_u64 v[12:13], v[12:13], 0, v[14:15]
	v_lshl_add_u64 v[18:19], s[10:11], 0, v[16:17]
	v_ashrrev_i32_e32 v21, 31, v20
	v_and_b32_e32 v32, 0x70, v29
	v_ashrrev_i32_e32 v29, 31, v28
	global_load_lds_dwordx4 v[8:9], off
	s_or_b32 m0, s1, 0x400
	s_add_i32 s9, s1, 0x4400
	v_lshl_add_u64 v[18:19], v[18:19], 0, v[14:15]
	v_lshlrev_b64 v[24:25], 11, v[20:21]
	v_lshlrev_b64 v[34:35], 11, v[28:29]
	global_load_lds_dwordx4 v[12:13], off
	s_mov_b32 m0, s9
	v_lshl_add_u64 v[22:23], v[22:23], 0, v[0:1]
	v_lshl_add_u64 v[26:27], s[10:11], 0, v[24:25]
	v_lshl_add_u64 v[36:37], s[10:11], 0, v[34:35]
	global_load_lds_dwordx4 v[18:19], off
	s_or_b32 m0, s1, 0x800
	s_add_i32 s10, s1, 0x4800
	v_lshl_add_u64 v[26:27], v[26:27], 0, v[0:1]
	v_mov_b32_e32 v33, v1
	global_load_lds_dwordx4 v[22:23], off
	s_mov_b32 m0, s10
	v_lshl_add_u64 v[30:31], v[30:31], 0, v[32:33]
	global_load_lds_dwordx4 v[26:27], off
	s_or_b32 m0, s1, 0xc00
	s_add_i32 s11, s1, 0x4c00
	v_lshl_add_u64 v[36:37], v[36:37], 0, v[32:33]
	global_load_lds_dwordx4 v[30:31], off
	s_mov_b32 m0, s11
	s_lshr_b32 s13, s12, 1
	global_load_lds_dwordx4 v[36:37], off
	v_and_b32_e32 v39, 31, v38
	s_and_b32 s13, s13, 0x1ffffc0
	v_or_b32_e32 v9, s13, v39
	v_cmp_gt_i64_e32 vcc, s[30:31], v[2:3]
	s_mul_i32 s13, s2, 0x7c0000
	s_add_u32 s6, s13, s6
	v_cndmask_b32_e32 v3, 0, v3, vcc
	v_cndmask_b32_e32 v2, v164, v2, vcc
	s_mul_hi_u32 s13, s2, 0x7c0000
	v_lshlrev_b64 v[2:3], 11, v[2:3]
	s_addc_u32 s7, s13, s7
	v_lshl_add_u64 v[66:67], s[4:5], 0, v[2:3]
	v_lshl_add_u64 v[2:3], s[6:7], 0, v[6:7]
	v_cmp_gt_i64_e32 vcc, s[30:31], v[10:11]
	v_lshl_add_u64 v[68:69], v[2:3], 0, v[0:1]
	v_bfe_u32 v4, v38, 5, 1
	v_cndmask_b32_e32 v3, 0, v11, vcc
	v_cndmask_b32_e32 v2, v164, v10, vcc
	v_lshlrev_b64 v[2:3], 11, v[2:3]
	v_lshrrev_b32_e32 v5, 1, v38
	v_lshl_add_u64 v[70:71], s[4:5], 0, v[2:3]
	v_lshl_add_u64 v[2:3], s[6:7], 0, v[16:17]
	v_cmp_gt_i64_e32 vcc, s[30:31], v[20:21]
	v_and_or_b32 v12, s12, 64, v39
	v_bitop3_b32 v5, v4, v5, 7 bitop3:0x78
	v_lshl_add_u64 v[72:73], v[2:3], 0, v[14:15]
	v_cndmask_b32_e32 v3, 0, v21, vcc
	v_cndmask_b32_e32 v2, v164, v20, vcc
	v_bfe_u32 v8, v38, 1, 3
	v_lshlrev_b32_e32 v9, 7, v9
	v_lshl_or_b32 v12, v12, 7, v163
	v_lshlrev_b32_e32 v5, 4, v5
	v_lshlrev_b64 v[2:3], 11, v[2:3]
	v_or_b32_e32 v84, v9, v5
	v_or_b32_e32 v85, v12, v5
	v_bitop3_b32 v5, v4, v8, 2 bitop3:0x36
	v_lshl_add_u64 v[74:75], s[4:5], 0, v[2:3]
	v_lshl_add_u64 v[2:3], s[6:7], 0, v[24:25]
	v_cmp_gt_i64_e32 vcc, s[30:31], v[28:29]
	v_lshlrev_b32_e32 v5, 4, v5
	v_lshl_add_u64 v[76:77], v[2:3], 0, v[0:1]
	v_cndmask_b32_e32 v3, 0, v29, vcc
	v_cndmask_b32_e32 v2, v164, v28, vcc
	s_waitcnt vmcnt(0)
	v_or_b32_e32 v86, v9, v5
	v_or_b32_e32 v87, v12, v5
	v_bitop3_b32 v5, v4, v8, 4 bitop3:0x36
	v_bitop3_b32 v4, v4, v8, 6 bitop3:0x36
	v_lshlrev_b64 v[2:3], 11, v[2:3]
	v_lshlrev_b32_e32 v5, 4, v5
	v_lshlrev_b32_e32 v4, 4, v4
	v_lshl_add_u64 v[78:79], s[4:5], 0, v[2:3]
	v_lshl_add_u64 v[2:3], s[6:7], 0, v[34:35]
	v_mov_b32_e32 v34, 0
	v_or_b32_e32 v88, v9, v5
	v_or_b32_e32 v89, v12, v5
	v_or_b32_e32 v90, v9, v4
	v_or_b32_e32 v91, v12, v4
	s_mov_b32 s12, 0
	v_bitop3_b32 v66, v66, v41, v40 bitop3:0xf6
	v_or_b32_e32 v70, v70, v14
	v_bitop3_b32 v74, v74, v41, v40 bitop3:0xf6
	v_or_b32_e32 v78, v78, v32
	v_lshl_add_u64 v[80:81], v[2:3], 0, v[32:33]
	s_add_i32 s6, s1, 0x8000
	s_add_i32 s7, s1, 0xc000
	s_add_i32 s13, s1, 0x8400
	s_add_i32 s14, s1, 0xc400
	s_add_i32 s15, s1, 0x8800
	s_add_i32 s16, s1, 0xc800
	s_add_i32 s17, s1, 0x8c00
	s_add_i32 s25, s1, 0xcc00
	v_mov_b32_e32 v35, v34
	v_mov_b32_e32 v36, v34
	v_mov_b32_e32 v37, v34
	v_mov_b32_e32 v38, v34
	v_mov_b32_e32 v39, v34
	v_mov_b32_e32 v40, v34
	v_mov_b32_e32 v41, v34
	v_mov_b32_e32 v42, v34
	v_mov_b32_e32 v43, v34
	v_mov_b32_e32 v44, v34
	v_mov_b32_e32 v45, v34
	v_mov_b32_e32 v46, v34
	v_mov_b32_e32 v47, v34
	v_mov_b32_e32 v48, v34
	v_mov_b32_e32 v49, v34
	v_mov_b32_e32 v2, v34
	v_mov_b32_e32 v3, v34
	v_mov_b32_e32 v4, v34
	v_mov_b32_e32 v5, v34
	v_mov_b32_e32 v6, v34
	v_mov_b32_e32 v7, v34
	v_mov_b32_e32 v8, v34
	v_mov_b32_e32 v9, v34
	v_mov_b32_e32 v10, v34
	v_mov_b32_e32 v11, v34
	v_mov_b32_e32 v12, v34
	v_mov_b32_e32 v13, v34
	v_mov_b32_e32 v14, v34
	v_mov_b32_e32 v15, v34
	v_mov_b32_e32 v16, v34
	v_mov_b32_e32 v17, v34
	v_mov_b32_e32 v50, v34
	v_mov_b32_e32 v51, v34
	v_mov_b32_e32 v52, v34
	v_mov_b32_e32 v53, v34
	v_mov_b32_e32 v54, v34
	v_mov_b32_e32 v55, v34
	v_mov_b32_e32 v56, v34
	v_mov_b32_e32 v57, v34
	v_mov_b32_e32 v58, v34
	v_mov_b32_e32 v59, v34
	v_mov_b32_e32 v60, v34
	v_mov_b32_e32 v61, v34
	v_mov_b32_e32 v62, v34
	v_mov_b32_e32 v63, v34
	v_mov_b32_e32 v64, v34
	v_mov_b32_e32 v65, v34
	v_mov_b32_e32 v18, v34
	v_mov_b32_e32 v19, v34
	v_mov_b32_e32 v20, v34
	v_mov_b32_e32 v21, v34
	v_mov_b32_e32 v22, v34
	v_mov_b32_e32 v23, v34
	v_mov_b32_e32 v24, v34
	v_mov_b32_e32 v25, v34
	v_mov_b32_e32 v26, v34
	v_mov_b32_e32 v27, v34
	v_mov_b32_e32 v28, v34
	v_mov_b32_e32 v29, v34
	v_mov_b32_e32 v30, v34
	v_mov_b32_e32 v31, v34
	v_mov_b32_e32 v32, v34
	v_mov_b32_e32 v33, v34
	s_waitcnt vmcnt(0) lgkmcnt(0)
	s_barrier
	v_lshl_add_u64 v[66:67], s[80:81], 0, v[66:67]
	v_lshl_add_u64 v[66:67], v[66:67], 0, s[64:65]
	v_lshl_add_u64 v[68:69], s[80:81], 0, v[68:69]
	v_lshl_add_u64 v[68:69], v[68:69], 0, s[66:67]
	v_lshl_add_u64 v[70:71], s[80:81], 0, v[70:71]
	v_lshl_add_u64 v[70:71], v[70:71], 0, s[64:65]
	v_lshl_add_u64 v[72:73], s[80:81], 0, v[72:73]
	v_lshl_add_u64 v[72:73], v[72:73], 0, s[66:67]
	v_lshl_add_u64 v[74:75], s[80:81], 0, v[74:75]
	v_lshl_add_u64 v[74:75], v[74:75], 0, s[64:65]
	v_lshl_add_u64 v[76:77], s[80:81], 0, v[76:77]
	v_lshl_add_u64 v[76:77], v[76:77], 0, s[66:67]
	v_lshl_add_u64 v[78:79], s[80:81], 0, v[78:79]
	v_lshl_add_u64 v[78:79], v[78:79], 0, s[64:65]
	v_lshl_add_u64 v[80:81], s[80:81], 0, v[80:81]
	v_lshl_add_u64 v[80:81], v[80:81], 0, s[66:67]
	s_mov_b64 s[26:27], 0x40000
	s_mov_b64 s[72:73], 0x3ff80
	s_mov_b32 m0, s6
	v_lshl_add_u64 v[82:83], v[66:67], 0, s[72:73]
	s_nop 0
	global_load_lds_dwordx4 v[82:83], off
	s_mov_b32 m0, s13
	v_lshl_add_u64 v[82:83], v[70:71], 0, s[72:73]
	s_nop 0
	global_load_lds_dwordx4 v[82:83], off
	s_mov_b32 m0, s15
	v_lshl_add_u64 v[82:83], v[74:75], 0, s[72:73]
	s_nop 0
	global_load_lds_dwordx4 v[82:83], off
	s_mov_b32 m0, s17
	v_lshl_add_u64 v[82:83], v[78:79], 0, s[72:73]
	s_nop 0
	global_load_lds_dwordx4 v[82:83], off
	s_mov_b32 m0, s7
	s_nop 0
	global_load_lds_dwordx4 v[68:69], off
	v_lshl_add_u64 v[68:69], v[68:69], 0, s[34:35]
	s_mov_b32 m0, s14
	s_nop 0
	global_load_lds_dwordx4 v[72:73], off
	v_lshl_add_u64 v[72:73], v[72:73], 0, s[34:35]
	s_mov_b32 m0, s16
	s_nop 0
	global_load_lds_dwordx4 v[76:77], off
	v_lshl_add_u64 v[76:77], v[76:77], 0, s[34:35]
	s_mov_b32 m0, s25
	s_nop 0
	global_load_lds_dwordx4 v[80:81], off
	v_lshl_add_u64 v[80:81], v[80:81], 0, s[34:35]
	v_mov_b32_e32 v104, 0
	v_mov_b32_e32 v105, 0
	v_mov_b32_e32 v106, 0
	v_mov_b32_e32 v107, 0
	v_mov_b32_e32 v108, 0
	v_mov_b32_e32 v109, 0
	v_mov_b32_e32 v110, 0
	v_mov_b32_e32 v111, 0
	v_mov_b32_e32 v112, 0
	v_mov_b32_e32 v113, 0
	v_mov_b32_e32 v114, 0
	v_mov_b32_e32 v115, 0
	v_mov_b32_e32 v116, 0
	v_mov_b32_e32 v117, 0
	v_mov_b32_e32 v118, 0
	v_mov_b32_e32 v119, 0
	v_mov_b32_e32 v128, 0
	v_mov_b32_e32 v129, 0
	v_mov_b32_e32 v130, 0
	v_mov_b32_e32 v131, 0
	v_mov_b32_e32 v132, 0
	v_mov_b32_e32 v133, 0
	v_mov_b32_e32 v134, 0
	v_mov_b32_e32 v135, 0
	v_mov_b32_e32 v136, 0
	v_mov_b32_e32 v137, 0
	v_mov_b32_e32 v138, 0
	v_mov_b32_e32 v139, 0
	v_mov_b32_e32 v140, 0
	v_mov_b32_e32 v141, 0
	v_mov_b32_e32 v142, 0
	v_mov_b32_e32 v143, 0
	v_mov_b32_e32 v196, 0
	v_mov_b32_e32 v197, 0
	v_mov_b32_e32 v198, 0
	v_mov_b32_e32 v199, 0
	v_mov_b32_e32 v200, 0
	v_mov_b32_e32 v201, 0
	v_mov_b32_e32 v202, 0
	v_mov_b32_e32 v203, 0
	v_mov_b32_e32 v204, 0
	v_mov_b32_e32 v205, 0
	v_mov_b32_e32 v206, 0
	v_mov_b32_e32 v207, 0
	v_mov_b32_e32 v208, 0
	v_mov_b32_e32 v209, 0
	v_mov_b32_e32 v210, 0
	v_mov_b32_e32 v211, 0
	v_mov_b32_e32 v236, 0
	v_mov_b32_e32 v237, 0
	v_mov_b32_e32 v238, 0
	v_mov_b32_e32 v239, 0
	v_mov_b32_e32 v240, 0
	v_mov_b32_e32 v241, 0
	v_mov_b32_e32 v242, 0
	v_mov_b32_e32 v243, 0
	v_mov_b32_e32 v244, 0
	v_mov_b32_e32 v245, 0
	v_mov_b32_e32 v246, 0
	v_mov_b32_e32 v247, 0
	v_mov_b32_e32 v248, 0
	v_mov_b32_e32 v249, 0
	v_mov_b32_e32 v250, 0
	v_mov_b32_e32 v251, 0
	s_mov_b32 s12, 0
	s_lshr_b32 s72, s1, 12
	s_cmp_eq_u32 s72, 1
	s_cbranch_scc1 .Lg1_loop_w1
	s_cmp_eq_u32 s72, 2
	s_cbranch_scc1 .Lg1_loop_w2
	s_cmp_eq_u32 s72, 3
	s_cbranch_scc1 .Lg1_loop_w3
.Lg1_loop:
	ds_read_b128 v[92:95], v84 offset:0
	ds_read_b128 v[96:99], v84 offset:4096
	ds_read_b128 v[188:191], v85 offset:0
	ds_read_b128 v[192:195], v85 offset:4096
	ds_read_b128 v[100:103], v86 offset:0
	ds_read_b128 v[144:147], v86 offset:4096
	ds_read_b128 v[212:215], v87 offset:0
	ds_read_b128 v[216:219], v87 offset:4096
	ds_read_b128 v[148:151], v88 offset:0
	ds_read_b128 v[152:155], v88 offset:4096
	ds_read_b128 v[220:223], v89 offset:0
	ds_read_b128 v[224:227], v89 offset:4096
	ds_read_b128 v[180:183], v90 offset:0
	ds_read_b128 v[184:187], v90 offset:4096
	ds_read_b128 v[228:231], v91 offset:0
	ds_read_b128 v[252:255], v91 offset:4096
	s_waitcnt lgkmcnt(0)
	s_barrier
	s_mov_b32 m0, s1
	v_mfma_f32_32x32x16_bf16 v[18:33], v[92:95], v[188:191], v[18:33]
	global_load_lds_dwordx4 v[66:67], off
	v_mfma_f32_32x32x16_bf16 v[50:65], v[92:95], v[192:195], v[50:65]
	v_mfma_f32_32x32x16_bf16 v[2:17], v[96:99], v[188:191], v[2:17]
	s_add_i32 m0, s1, 0x400
	v_mfma_f32_32x32x16_bf16 v[34:49], v[96:99], v[192:195], v[34:49]
	global_load_lds_dwordx4 v[70:71], off
	v_mfma_f32_32x32x16_bf16 v[18:33], v[100:103], v[212:215], v[18:33]
	s_add_i32 m0, s1, 0x800
	v_mfma_f32_32x32x16_bf16 v[50:65], v[100:103], v[216:219], v[50:65]
	global_load_lds_dwordx4 v[74:75], off
	v_mfma_f32_32x32x16_bf16 v[2:17], v[144:147], v[212:215], v[2:17]
	v_mfma_f32_32x32x16_bf16 v[34:49], v[144:147], v[216:219], v[34:49]
	s_add_i32 m0, s1, 0xc00
	v_mfma_f32_32x32x16_bf16 v[18:33], v[148:151], v[220:223], v[18:33]
	global_load_lds_dwordx4 v[78:79], off
	v_mfma_f32_32x32x16_bf16 v[50:65], v[148:151], v[224:227], v[50:65]
	v_mfma_f32_32x32x16_bf16 v[2:17], v[152:155], v[220:223], v[2:17]
	s_mov_b32 m0, s8
	v_mfma_f32_32x32x16_bf16 v[34:49], v[152:155], v[224:227], v[34:49]
	global_load_lds_dwordx4 v[68:69], off
	v_lshl_add_u64 v[68:69], v[68:69], 0, s[34:35]
	v_mfma_f32_32x32x16_bf16 v[18:33], v[180:183], v[228:231], v[18:33]
	s_mov_b32 m0, s9
	v_mfma_f32_32x32x16_bf16 v[50:65], v[180:183], v[252:255], v[50:65]
	global_load_lds_dwordx4 v[72:73], off
	v_lshl_add_u64 v[72:73], v[72:73], 0, s[34:35]
	v_mfma_f32_32x32x16_bf16 v[2:17], v[184:187], v[228:231], v[2:17]
	v_mfma_f32_32x32x16_bf16 v[34:49], v[184:187], v[252:255], v[34:49]
	s_waitcnt vmcnt(6)
	s_barrier
	ds_read_b128 v[92:95], v84 offset:32768
	ds_read_b128 v[96:99], v84 offset:36864
	ds_read_b128 v[100:103], v86 offset:32768
	ds_read_b128 v[144:147], v86 offset:36864
	ds_read_b128 v[148:151], v88 offset:32768
	ds_read_b128 v[152:155], v88 offset:36864
	ds_read_b128 v[180:183], v90 offset:32768
	ds_read_b128 v[184:187], v90 offset:36864
	s_waitcnt lgkmcnt(0)
	s_barrier
	s_mov_b32 m0, s6
	v_lshl_add_u64 v[82:83], v[66:67], 0, s[26:27]
	v_mfma_f32_32x32x16_bf16 v[104:119], v[92:95], v[188:191], v[104:119]
	global_load_lds_dwordx4 v[82:83], off
	v_lshl_add_u64 v[66:67], v[66:67], 0, s[34:35]
	v_mfma_f32_32x32x16_bf16 v[128:143], v[92:95], v[192:195], v[128:143]
	v_mfma_f32_32x32x16_bf16 v[196:211], v[96:99], v[188:191], v[196:211]
	s_mov_b32 m0, s13
	v_lshl_add_u64 v[82:83], v[70:71], 0, s[26:27]
	v_mfma_f32_32x32x16_bf16 v[236:251], v[96:99], v[192:195], v[236:251]
	global_load_lds_dwordx4 v[82:83], off
	v_lshl_add_u64 v[70:71], v[70:71], 0, s[34:35]
	v_mfma_f32_32x32x16_bf16 v[104:119], v[100:103], v[212:215], v[104:119]
	s_mov_b32 m0, s15
	v_lshl_add_u64 v[82:83], v[74:75], 0, s[26:27]
	v_mfma_f32_32x32x16_bf16 v[128:143], v[100:103], v[216:219], v[128:143]
	global_load_lds_dwordx4 v[82:83], off
	v_lshl_add_u64 v[74:75], v[74:75], 0, s[34:35]
	v_mfma_f32_32x32x16_bf16 v[196:211], v[144:147], v[212:215], v[196:211]
	v_mfma_f32_32x32x16_bf16 v[236:251], v[144:147], v[216:219], v[236:251]
	s_mov_b32 m0, s17
	v_lshl_add_u64 v[82:83], v[78:79], 0, s[26:27]
	v_mfma_f32_32x32x16_bf16 v[104:119], v[148:151], v[220:223], v[104:119]
	global_load_lds_dwordx4 v[82:83], off
	v_lshl_add_u64 v[78:79], v[78:79], 0, s[34:35]
	v_mfma_f32_32x32x16_bf16 v[128:143], v[148:151], v[224:227], v[128:143]
	v_mfma_f32_32x32x16_bf16 v[196:211], v[152:155], v[220:223], v[196:211]
	s_mov_b32 m0, s10
	v_mfma_f32_32x32x16_bf16 v[236:251], v[152:155], v[224:227], v[236:251]
	global_load_lds_dwordx4 v[76:77], off
	v_lshl_add_u64 v[76:77], v[76:77], 0, s[34:35]
	v_mfma_f32_32x32x16_bf16 v[104:119], v[180:183], v[228:231], v[104:119]
	s_mov_b32 m0, s11
	v_mfma_f32_32x32x16_bf16 v[128:143], v[180:183], v[252:255], v[128:143]
	global_load_lds_dwordx4 v[80:81], off
	v_lshl_add_u64 v[80:81], v[80:81], 0, s[34:35]
	v_mfma_f32_32x32x16_bf16 v[196:211], v[184:187], v[228:231], v[196:211]
	v_mfma_f32_32x32x16_bf16 v[236:251], v[184:187], v[252:255], v[236:251]
	s_waitcnt vmcnt(6)
	s_barrier
	ds_read_b128 v[92:95], v84 offset:0
	ds_read_b128 v[96:99], v84 offset:4096
	ds_read_b128 v[188:191], v85 offset:32768
	ds_read_b128 v[192:195], v85 offset:36864
	ds_read_b128 v[100:103], v86 offset:0
	ds_read_b128 v[144:147], v86 offset:4096
	ds_read_b128 v[212:215], v87 offset:32768
	ds_read_b128 v[216:219], v87 offset:36864
	ds_read_b128 v[148:151], v88 offset:0
	ds_read_b128 v[152:155], v88 offset:4096
	ds_read_b128 v[220:223], v89 offset:32768
	ds_read_b128 v[224:227], v89 offset:36864
	ds_read_b128 v[180:183], v90 offset:0
	ds_read_b128 v[184:187], v90 offset:4096
	ds_read_b128 v[228:231], v91 offset:32768
	ds_read_b128 v[252:255], v91 offset:36864
	s_waitcnt lgkmcnt(0)
	s_barrier
	s_mov_b32 m0, s1
	v_mfma_f32_32x32x16_bf16 v[18:33], v[92:95], v[188:191], v[18:33]
	global_load_lds_dwordx4 v[66:67], off
	v_mfma_f32_32x32x16_bf16 v[50:65], v[92:95], v[192:195], v[50:65]
	v_mfma_f32_32x32x16_bf16 v[2:17], v[96:99], v[188:191], v[2:17]
	s_add_i32 m0, s1, 0x400
	v_mfma_f32_32x32x16_bf16 v[34:49], v[96:99], v[192:195], v[34:49]
	global_load_lds_dwordx4 v[70:71], off
	v_mfma_f32_32x32x16_bf16 v[18:33], v[100:103], v[212:215], v[18:33]
	s_add_i32 m0, s1, 0x800
	v_mfma_f32_32x32x16_bf16 v[50:65], v[100:103], v[216:219], v[50:65]
	global_load_lds_dwordx4 v[74:75], off
	v_mfma_f32_32x32x16_bf16 v[2:17], v[144:147], v[212:215], v[2:17]
	v_mfma_f32_32x32x16_bf16 v[34:49], v[144:147], v[216:219], v[34:49]
	s_add_i32 m0, s1, 0xc00
	v_mfma_f32_32x32x16_bf16 v[18:33], v[148:151], v[220:223], v[18:33]
	global_load_lds_dwordx4 v[78:79], off
	v_mfma_f32_32x32x16_bf16 v[50:65], v[148:151], v[224:227], v[50:65]
	v_mfma_f32_32x32x16_bf16 v[2:17], v[152:155], v[220:223], v[2:17]
	s_mov_b32 m0, s7
	v_mfma_f32_32x32x16_bf16 v[34:49], v[152:155], v[224:227], v[34:49]
	global_load_lds_dwordx4 v[68:69], off
	v_lshl_add_u64 v[68:69], v[68:69], 0, s[34:35]
	v_mfma_f32_32x32x16_bf16 v[18:33], v[180:183], v[228:231], v[18:33]
	s_mov_b32 m0, s14
	v_mfma_f32_32x32x16_bf16 v[50:65], v[180:183], v[252:255], v[50:65]
	global_load_lds_dwordx4 v[72:73], off
	v_lshl_add_u64 v[72:73], v[72:73], 0, s[34:35]
	v_mfma_f32_32x32x16_bf16 v[2:17], v[184:187], v[228:231], v[2:17]
	v_mfma_f32_32x32x16_bf16 v[34:49], v[184:187], v[252:255], v[34:49]
	s_waitcnt vmcnt(6)
	s_barrier
	ds_read_b128 v[92:95], v84 offset:32768
	ds_read_b128 v[96:99], v84 offset:36864
	ds_read_b128 v[100:103], v86 offset:32768
	ds_read_b128 v[144:147], v86 offset:36864
	ds_read_b128 v[148:151], v88 offset:32768
	ds_read_b128 v[152:155], v88 offset:36864
	ds_read_b128 v[180:183], v90 offset:32768
	ds_read_b128 v[184:187], v90 offset:36864
	s_waitcnt lgkmcnt(0)
	s_barrier
	s_mov_b32 m0, s6
	v_lshl_add_u64 v[82:83], v[66:67], 0, s[26:27]
	v_mfma_f32_32x32x16_bf16 v[104:119], v[92:95], v[188:191], v[104:119]
	global_load_lds_dwordx4 v[82:83], off
	v_lshl_add_u64 v[66:67], v[66:67], 0, s[34:35]
	v_mfma_f32_32x32x16_bf16 v[128:143], v[92:95], v[192:195], v[128:143]
	v_mfma_f32_32x32x16_bf16 v[196:211], v[96:99], v[188:191], v[196:211]
	s_mov_b32 m0, s13
	v_lshl_add_u64 v[82:83], v[70:71], 0, s[26:27]
	v_mfma_f32_32x32x16_bf16 v[236:251], v[96:99], v[192:195], v[236:251]
	global_load_lds_dwordx4 v[82:83], off
	v_lshl_add_u64 v[70:71], v[70:71], 0, s[34:35]
	v_mfma_f32_32x32x16_bf16 v[104:119], v[100:103], v[212:215], v[104:119]
	s_mov_b32 m0, s15
	v_lshl_add_u64 v[82:83], v[74:75], 0, s[26:27]
	v_mfma_f32_32x32x16_bf16 v[128:143], v[100:103], v[216:219], v[128:143]
	global_load_lds_dwordx4 v[82:83], off
	v_lshl_add_u64 v[74:75], v[74:75], 0, s[34:35]
	v_mfma_f32_32x32x16_bf16 v[196:211], v[144:147], v[212:215], v[196:211]
	v_mfma_f32_32x32x16_bf16 v[236:251], v[144:147], v[216:219], v[236:251]
	s_mov_b32 m0, s17
	v_lshl_add_u64 v[82:83], v[78:79], 0, s[26:27]
	v_mfma_f32_32x32x16_bf16 v[104:119], v[148:151], v[220:223], v[104:119]
	global_load_lds_dwordx4 v[82:83], off
	v_lshl_add_u64 v[78:79], v[78:79], 0, s[34:35]
	v_mfma_f32_32x32x16_bf16 v[128:143], v[148:151], v[224:227], v[128:143]
	v_mfma_f32_32x32x16_bf16 v[196:211], v[152:155], v[220:223], v[196:211]
	s_mov_b32 m0, s16
	v_mfma_f32_32x32x16_bf16 v[236:251], v[152:155], v[224:227], v[236:251]
	global_load_lds_dwordx4 v[76:77], off
	v_lshl_add_u64 v[76:77], v[76:77], 0, s[34:35]
	v_mfma_f32_32x32x16_bf16 v[104:119], v[180:183], v[228:231], v[104:119]
	s_mov_b32 m0, s25
	v_mfma_f32_32x32x16_bf16 v[128:143], v[180:183], v[252:255], v[128:143]
	global_load_lds_dwordx4 v[80:81], off
	v_lshl_add_u64 v[80:81], v[80:81], 0, s[34:35]
	v_mfma_f32_32x32x16_bf16 v[196:211], v[184:187], v[228:231], v[196:211]
	v_mfma_f32_32x32x16_bf16 v[236:251], v[184:187], v[252:255], v[236:251]
	s_waitcnt vmcnt(6)
	s_barrier
	s_add_i32 s12, s12, 2
	s_cmp_lt_u32 s12, 14
	s_cbranch_scc1 .Lg1_loop
	ds_read_b128 v[92:95], v84 offset:0
	ds_read_b128 v[96:99], v84 offset:4096
	ds_read_b128 v[188:191], v85 offset:0
	ds_read_b128 v[192:195], v85 offset:4096
	ds_read_b128 v[100:103], v86 offset:0
	ds_read_b128 v[144:147], v86 offset:4096
	ds_read_b128 v[212:215], v87 offset:0
	ds_read_b128 v[216:219], v87 offset:4096
	ds_read_b128 v[148:151], v88 offset:0
	ds_read_b128 v[152:155], v88 offset:4096
	ds_read_b128 v[220:223], v89 offset:0
	ds_read_b128 v[224:227], v89 offset:4096
	ds_read_b128 v[180:183], v90 offset:0
	ds_read_b128 v[184:187], v90 offset:4096
	ds_read_b128 v[228:231], v91 offset:0
	ds_read_b128 v[252:255], v91 offset:4096
	s_waitcnt lgkmcnt(0)
	s_barrier
	s_mov_b32 m0, s1
	v_mfma_f32_32x32x16_bf16 v[18:33], v[92:95], v[188:191], v[18:33]
	global_load_lds_dwordx4 v[66:67], off
	v_mfma_f32_32x32x16_bf16 v[50:65], v[92:95], v[192:195], v[50:65]
	v_mfma_f32_32x32x16_bf16 v[2:17], v[96:99], v[188:191], v[2:17]
	s_add_i32 m0, s1, 0x400
	v_mfma_f32_32x32x16_bf16 v[34:49], v[96:99], v[192:195], v[34:49]
	global_load_lds_dwordx4 v[70:71], off
	v_mfma_f32_32x32x16_bf16 v[18:33], v[100:103], v[212:215], v[18:33]
	v_mfma_f32_32x32x16_bf16 v[50:65], v[100:103], v[216:219], v[50:65]
	v_mfma_f32_32x32x16_bf16 v[2:17], v[144:147], v[212:215], v[2:17]
	v_mfma_f32_32x32x16_bf16 v[34:49], v[144:147], v[216:219], v[34:49]
	s_add_i32 m0, s1, 0x800
	v_mfma_f32_32x32x16_bf16 v[18:33], v[148:151], v[220:223], v[18:33]
	global_load_lds_dwordx4 v[74:75], off
	v_mfma_f32_32x32x16_bf16 v[50:65], v[148:151], v[224:227], v[50:65]
	v_mfma_f32_32x32x16_bf16 v[2:17], v[152:155], v[220:223], v[2:17]
	s_add_i32 m0, s1, 0xc00
	v_mfma_f32_32x32x16_bf16 v[34:49], v[152:155], v[224:227], v[34:49]
	global_load_lds_dwordx4 v[78:79], off
	v_mfma_f32_32x32x16_bf16 v[18:33], v[180:183], v[228:231], v[18:33]
	v_mfma_f32_32x32x16_bf16 v[50:65], v[180:183], v[252:255], v[50:65]
	v_mfma_f32_32x32x16_bf16 v[2:17], v[184:187], v[228:231], v[2:17]
	v_mfma_f32_32x32x16_bf16 v[34:49], v[184:187], v[252:255], v[34:49]
	s_waitcnt vmcnt(4)
	s_barrier
	ds_read_b128 v[92:95], v84 offset:32768
	ds_read_b128 v[96:99], v84 offset:36864
	ds_read_b128 v[100:103], v86 offset:32768
	ds_read_b128 v[144:147], v86 offset:36864
	ds_read_b128 v[148:151], v88 offset:32768
	ds_read_b128 v[152:155], v88 offset:36864
	ds_read_b128 v[180:183], v90 offset:32768
	ds_read_b128 v[184:187], v90 offset:36864
	s_waitcnt lgkmcnt(0)
	s_barrier
	s_mov_b32 m0, s6
	v_lshl_add_u64 v[82:83], v[66:67], 0, s[26:27]
	v_mfma_f32_32x32x16_bf16 v[104:119], v[92:95], v[188:191], v[104:119]
	global_load_lds_dwordx4 v[82:83], off
	v_lshl_add_u64 v[66:67], v[66:67], 0, s[34:35]
	v_mfma_f32_32x32x16_bf16 v[128:143], v[92:95], v[192:195], v[128:143]
	v_mfma_f32_32x32x16_bf16 v[196:211], v[96:99], v[188:191], v[196:211]
	s_mov_b32 m0, s13
	v_lshl_add_u64 v[82:83], v[70:71], 0, s[26:27]
	v_mfma_f32_32x32x16_bf16 v[236:251], v[96:99], v[192:195], v[236:251]
	global_load_lds_dwordx4 v[82:83], off
	v_lshl_add_u64 v[70:71], v[70:71], 0, s[34:35]
	v_mfma_f32_32x32x16_bf16 v[104:119], v[100:103], v[212:215], v[104:119]
	v_mfma_f32_32x32x16_bf16 v[128:143], v[100:103], v[216:219], v[128:143]
	v_mfma_f32_32x32x16_bf16 v[196:211], v[144:147], v[212:215], v[196:211]
	v_mfma_f32_32x32x16_bf16 v[236:251], v[144:147], v[216:219], v[236:251]
	s_mov_b32 m0, s15
	v_lshl_add_u64 v[82:83], v[74:75], 0, s[26:27]
	v_mfma_f32_32x32x16_bf16 v[104:119], v[148:151], v[220:223], v[104:119]
	global_load_lds_dwordx4 v[82:83], off
	v_lshl_add_u64 v[74:75], v[74:75], 0, s[34:35]
	v_mfma_f32_32x32x16_bf16 v[128:143], v[148:151], v[224:227], v[128:143]
	v_mfma_f32_32x32x16_bf16 v[196:211], v[152:155], v[220:223], v[196:211]
	s_mov_b32 m0, s17
	v_lshl_add_u64 v[82:83], v[78:79], 0, s[26:27]
	v_mfma_f32_32x32x16_bf16 v[236:251], v[152:155], v[224:227], v[236:251]
	global_load_lds_dwordx4 v[82:83], off
	v_lshl_add_u64 v[78:79], v[78:79], 0, s[34:35]
	v_mfma_f32_32x32x16_bf16 v[104:119], v[180:183], v[228:231], v[104:119]
	v_mfma_f32_32x32x16_bf16 v[128:143], v[180:183], v[252:255], v[128:143]
	v_mfma_f32_32x32x16_bf16 v[196:211], v[184:187], v[228:231], v[196:211]
	v_mfma_f32_32x32x16_bf16 v[236:251], v[184:187], v[252:255], v[236:251]
	s_waitcnt vmcnt(4)
	s_barrier
	ds_read_b128 v[92:95], v84 offset:0
	ds_read_b128 v[96:99], v84 offset:4096
	ds_read_b128 v[188:191], v85 offset:32768
	ds_read_b128 v[192:195], v85 offset:36864
	ds_read_b128 v[100:103], v86 offset:0
	ds_read_b128 v[144:147], v86 offset:4096
	ds_read_b128 v[212:215], v87 offset:32768
	ds_read_b128 v[216:219], v87 offset:36864
	ds_read_b128 v[148:151], v88 offset:0
	ds_read_b128 v[152:155], v88 offset:4096
	ds_read_b128 v[220:223], v89 offset:32768
	ds_read_b128 v[224:227], v89 offset:36864
	ds_read_b128 v[180:183], v90 offset:0
	ds_read_b128 v[184:187], v90 offset:4096
	ds_read_b128 v[228:231], v91 offset:32768
	ds_read_b128 v[252:255], v91 offset:36864
	s_waitcnt lgkmcnt(0)
	s_barrier
	v_mfma_f32_32x32x16_bf16 v[18:33], v[92:95], v[188:191], v[18:33]
	v_mfma_f32_32x32x16_bf16 v[50:65], v[92:95], v[192:195], v[50:65]
	v_mfma_f32_32x32x16_bf16 v[2:17], v[96:99], v[188:191], v[2:17]
	v_mfma_f32_32x32x16_bf16 v[34:49], v[96:99], v[192:195], v[34:49]
	v_mfma_f32_32x32x16_bf16 v[18:33], v[100:103], v[212:215], v[18:33]
	v_mfma_f32_32x32x16_bf16 v[50:65], v[100:103], v[216:219], v[50:65]
	v_mfma_f32_32x32x16_bf16 v[2:17], v[144:147], v[212:215], v[2:17]
	v_mfma_f32_32x32x16_bf16 v[34:49], v[144:147], v[216:219], v[34:49]
	v_mfma_f32_32x32x16_bf16 v[18:33], v[148:151], v[220:223], v[18:33]
	v_mfma_f32_32x32x16_bf16 v[50:65], v[148:151], v[224:227], v[50:65]
	v_mfma_f32_32x32x16_bf16 v[2:17], v[152:155], v[220:223], v[2:17]
	v_mfma_f32_32x32x16_bf16 v[34:49], v[152:155], v[224:227], v[34:49]
	v_mfma_f32_32x32x16_bf16 v[18:33], v[180:183], v[228:231], v[18:33]
	v_mfma_f32_32x32x16_bf16 v[50:65], v[180:183], v[252:255], v[50:65]
	v_mfma_f32_32x32x16_bf16 v[2:17], v[184:187], v[228:231], v[2:17]
	v_mfma_f32_32x32x16_bf16 v[34:49], v[184:187], v[252:255], v[34:49]
	s_waitcnt vmcnt(0)
	s_barrier
	ds_read_b128 v[92:95], v84 offset:32768
	ds_read_b128 v[96:99], v84 offset:36864
	ds_read_b128 v[100:103], v86 offset:32768
	ds_read_b128 v[144:147], v86 offset:36864
	ds_read_b128 v[148:151], v88 offset:32768
	ds_read_b128 v[152:155], v88 offset:36864
	ds_read_b128 v[180:183], v90 offset:32768
	ds_read_b128 v[184:187], v90 offset:36864
	s_waitcnt lgkmcnt(0)
	s_barrier
	v_mfma_f32_32x32x16_bf16 v[104:119], v[92:95], v[188:191], v[104:119]
	v_mfma_f32_32x32x16_bf16 v[128:143], v[92:95], v[192:195], v[128:143]
	v_mfma_f32_32x32x16_bf16 v[196:211], v[96:99], v[188:191], v[196:211]
	v_mfma_f32_32x32x16_bf16 v[236:251], v[96:99], v[192:195], v[236:251]
	v_mfma_f32_32x32x16_bf16 v[104:119], v[100:103], v[212:215], v[104:119]
	v_mfma_f32_32x32x16_bf16 v[128:143], v[100:103], v[216:219], v[128:143]
	v_mfma_f32_32x32x16_bf16 v[196:211], v[144:147], v[212:215], v[196:211]
	v_mfma_f32_32x32x16_bf16 v[236:251], v[144:147], v[216:219], v[236:251]
	v_mfma_f32_32x32x16_bf16 v[104:119], v[148:151], v[220:223], v[104:119]
	v_mfma_f32_32x32x16_bf16 v[128:143], v[148:151], v[224:227], v[128:143]
	v_mfma_f32_32x32x16_bf16 v[196:211], v[152:155], v[220:223], v[196:211]
	v_mfma_f32_32x32x16_bf16 v[236:251], v[152:155], v[224:227], v[236:251]
	v_mfma_f32_32x32x16_bf16 v[104:119], v[180:183], v[228:231], v[104:119]
	v_mfma_f32_32x32x16_bf16 v[128:143], v[180:183], v[252:255], v[128:143]
	v_mfma_f32_32x32x16_bf16 v[196:211], v[184:187], v[228:231], v[196:211]
	v_mfma_f32_32x32x16_bf16 v[236:251], v[184:187], v[252:255], v[236:251]
	s_waitcnt vmcnt(0) lgkmcnt(0)
	s_barrier
	s_branch .LBB0_187
.Lg1_loop_w1:
	ds_read_b128 v[92:95], v84 offset:0
	ds_read_b128 v[96:99], v84 offset:4096
	ds_read_b128 v[188:191], v85 offset:0
	ds_read_b128 v[192:195], v85 offset:4096
	ds_read_b128 v[100:103], v86 offset:0
	ds_read_b128 v[144:147], v86 offset:4096
	ds_read_b128 v[212:215], v87 offset:0
	ds_read_b128 v[216:219], v87 offset:4096
	ds_read_b128 v[148:151], v88 offset:0
	ds_read_b128 v[152:155], v88 offset:4096
	ds_read_b128 v[220:223], v89 offset:0
	ds_read_b128 v[224:227], v89 offset:4096
	ds_read_b128 v[180:183], v90 offset:0
	ds_read_b128 v[184:187], v90 offset:4096
	ds_read_b128 v[228:231], v91 offset:0
	ds_read_b128 v[252:255], v91 offset:4096
	s_waitcnt lgkmcnt(0)
	s_barrier
	v_mfma_f32_32x32x16_bf16 v[18:33], v[92:95], v[188:191], v[18:33]
	s_mov_b32 m0, s1
	v_mfma_f32_32x32x16_bf16 v[50:65], v[92:95], v[192:195], v[50:65]
	global_load_lds_dwordx4 v[66:67], off
	v_mfma_f32_32x32x16_bf16 v[2:17], v[96:99], v[188:191], v[2:17]
	s_add_i32 m0, s1, 0x400
	v_mfma_f32_32x32x16_bf16 v[34:49], v[96:99], v[192:195], v[34:49]
	global_load_lds_dwordx4 v[70:71], off
	v_mfma_f32_32x32x16_bf16 v[18:33], v[100:103], v[212:215], v[18:33]
	v_mfma_f32_32x32x16_bf16 v[50:65], v[100:103], v[216:219], v[50:65]
	s_add_i32 m0, s1, 0x800
	v_mfma_f32_32x32x16_bf16 v[2:17], v[144:147], v[212:215], v[2:17]
	global_load_lds_dwordx4 v[74:75], off
	v_mfma_f32_32x32x16_bf16 v[34:49], v[144:147], v[216:219], v[34:49]
	v_mfma_f32_32x32x16_bf16 v[18:33], v[148:151], v[220:223], v[18:33]
	s_add_i32 m0, s1, 0xc00
	v_mfma_f32_32x32x16_bf16 v[50:65], v[148:151], v[224:227], v[50:65]
	global_load_lds_dwordx4 v[78:79], off
	v_mfma_f32_32x32x16_bf16 v[2:17], v[152:155], v[220:223], v[2:17]
	s_mov_b32 m0, s8
	v_mfma_f32_32x32x16_bf16 v[34:49], v[152:155], v[224:227], v[34:49]
	global_load_lds_dwordx4 v[68:69], off
	v_lshl_add_u64 v[68:69], v[68:69], 0, s[34:35]
	v_mfma_f32_32x32x16_bf16 v[18:33], v[180:183], v[228:231], v[18:33]
	v_mfma_f32_32x32x16_bf16 v[50:65], v[180:183], v[252:255], v[50:65]
	s_mov_b32 m0, s9
	v_mfma_f32_32x32x16_bf16 v[2:17], v[184:187], v[228:231], v[2:17]
	global_load_lds_dwordx4 v[72:73], off
	v_lshl_add_u64 v[72:73], v[72:73], 0, s[34:35]
	v_mfma_f32_32x32x16_bf16 v[34:49], v[184:187], v[252:255], v[34:49]
	s_waitcnt vmcnt(6)
	s_barrier
	ds_read_b128 v[92:95], v84 offset:32768
	ds_read_b128 v[96:99], v84 offset:36864
	ds_read_b128 v[100:103], v86 offset:32768
	ds_read_b128 v[144:147], v86 offset:36864
	ds_read_b128 v[148:151], v88 offset:32768
	ds_read_b128 v[152:155], v88 offset:36864
	ds_read_b128 v[180:183], v90 offset:32768
	ds_read_b128 v[184:187], v90 offset:36864
	s_waitcnt lgkmcnt(0)
	s_barrier
	v_mfma_f32_32x32x16_bf16 v[104:119], v[92:95], v[188:191], v[104:119]
	s_mov_b32 m0, s6
	v_lshl_add_u64 v[82:83], v[66:67], 0, s[26:27]
	v_mfma_f32_32x32x16_bf16 v[128:143], v[92:95], v[192:195], v[128:143]
	global_load_lds_dwordx4 v[82:83], off
	v_lshl_add_u64 v[66:67], v[66:67], 0, s[34:35]
	v_mfma_f32_32x32x16_bf16 v[196:211], v[96:99], v[188:191], v[196:211]
	s_mov_b32 m0, s13
	v_lshl_add_u64 v[82:83], v[70:71], 0, s[26:27]
	v_mfma_f32_32x32x16_bf16 v[236:251], v[96:99], v[192:195], v[236:251]
	global_load_lds_dwordx4 v[82:83], off
	v_lshl_add_u64 v[70:71], v[70:71], 0, s[34:35]
	v_mfma_f32_32x32x16_bf16 v[104:119], v[100:103], v[212:215], v[104:119]
	v_mfma_f32_32x32x16_bf16 v[128:143], v[100:103], v[216:219], v[128:143]
	s_mov_b32 m0, s15
	v_lshl_add_u64 v[82:83], v[74:75], 0, s[26:27]
	v_mfma_f32_32x32x16_bf16 v[196:211], v[144:147], v[212:215], v[196:211]
	global_load_lds_dwordx4 v[82:83], off
	v_lshl_add_u64 v[74:75], v[74:75], 0, s[34:35]
	v_mfma_f32_32x32x16_bf16 v[236:251], v[144:147], v[216:219], v[236:251]
	v_mfma_f32_32x32x16_bf16 v[104:119], v[148:151], v[220:223], v[104:119]
	s_mov_b32 m0, s17
	v_lshl_add_u64 v[82:83], v[78:79], 0, s[26:27]
	v_mfma_f32_32x32x16_bf16 v[128:143], v[148:151], v[224:227], v[128:143]
	global_load_lds_dwordx4 v[82:83], off
	v_lshl_add_u64 v[78:79], v[78:79], 0, s[34:35]
	v_mfma_f32_32x32x16_bf16 v[196:211], v[152:155], v[220:223], v[196:211]
	s_mov_b32 m0, s10
	v_mfma_f32_32x32x16_bf16 v[236:251], v[152:155], v[224:227], v[236:251]
	global_load_lds_dwordx4 v[76:77], off
	v_lshl_add_u64 v[76:77], v[76:77], 0, s[34:35]
	v_mfma_f32_32x32x16_bf16 v[104:119], v[180:183], v[228:231], v[104:119]
	v_mfma_f32_32x32x16_bf16 v[128:143], v[180:183], v[252:255], v[128:143]
	s_mov_b32 m0, s11
	v_mfma_f32_32x32x16_bf16 v[196:211], v[184:187], v[228:231], v[196:211]
	global_load_lds_dwordx4 v[80:81], off
	v_lshl_add_u64 v[80:81], v[80:81], 0, s[34:35]
	v_mfma_f32_32x32x16_bf16 v[236:251], v[184:187], v[252:255], v[236:251]
	s_waitcnt vmcnt(6)
	s_barrier
	ds_read_b128 v[92:95], v84 offset:0
	ds_read_b128 v[96:99], v84 offset:4096
	ds_read_b128 v[188:191], v85 offset:32768
	ds_read_b128 v[192:195], v85 offset:36864
	ds_read_b128 v[100:103], v86 offset:0
	ds_read_b128 v[144:147], v86 offset:4096
	ds_read_b128 v[212:215], v87 offset:32768
	ds_read_b128 v[216:219], v87 offset:36864
	ds_read_b128 v[148:151], v88 offset:0
	ds_read_b128 v[152:155], v88 offset:4096
	ds_read_b128 v[220:223], v89 offset:32768
	ds_read_b128 v[224:227], v89 offset:36864
	ds_read_b128 v[180:183], v90 offset:0
	ds_read_b128 v[184:187], v90 offset:4096
	ds_read_b128 v[228:231], v91 offset:32768
	ds_read_b128 v[252:255], v91 offset:36864
	s_waitcnt lgkmcnt(0)
	s_barrier
	v_mfma_f32_32x32x16_bf16 v[18:33], v[92:95], v[188:191], v[18:33]
	s_mov_b32 m0, s1
	v_mfma_f32_32x32x16_bf16 v[50:65], v[92:95], v[192:195], v[50:65]
	global_load_lds_dwordx4 v[66:67], off
	v_mfma_f32_32x32x16_bf16 v[2:17], v[96:99], v[188:191], v[2:17]
	s_add_i32 m0, s1, 0x400
	v_mfma_f32_32x32x16_bf16 v[34:49], v[96:99], v[192:195], v[34:49]
	global_load_lds_dwordx4 v[70:71], off
	v_mfma_f32_32x32x16_bf16 v[18:33], v[100:103], v[212:215], v[18:33]
	v_mfma_f32_32x32x16_bf16 v[50:65], v[100:103], v[216:219], v[50:65]
	s_add_i32 m0, s1, 0x800
	v_mfma_f32_32x32x16_bf16 v[2:17], v[144:147], v[212:215], v[2:17]
	global_load_lds_dwordx4 v[74:75], off
	v_mfma_f32_32x32x16_bf16 v[34:49], v[144:147], v[216:219], v[34:49]
	v_mfma_f32_32x32x16_bf16 v[18:33], v[148:151], v[220:223], v[18:33]
	s_add_i32 m0, s1, 0xc00
	v_mfma_f32_32x32x16_bf16 v[50:65], v[148:151], v[224:227], v[50:65]
	global_load_lds_dwordx4 v[78:79], off
	v_mfma_f32_32x32x16_bf16 v[2:17], v[152:155], v[220:223], v[2:17]
	s_mov_b32 m0, s7
	v_mfma_f32_32x32x16_bf16 v[34:49], v[152:155], v[224:227], v[34:49]
	global_load_lds_dwordx4 v[68:69], off
	v_lshl_add_u64 v[68:69], v[68:69], 0, s[34:35]
	v_mfma_f32_32x32x16_bf16 v[18:33], v[180:183], v[228:231], v[18:33]
	v_mfma_f32_32x32x16_bf16 v[50:65], v[180:183], v[252:255], v[50:65]
	s_mov_b32 m0, s14
	v_mfma_f32_32x32x16_bf16 v[2:17], v[184:187], v[228:231], v[2:17]
	global_load_lds_dwordx4 v[72:73], off
	v_lshl_add_u64 v[72:73], v[72:73], 0, s[34:35]
	v_mfma_f32_32x32x16_bf16 v[34:49], v[184:187], v[252:255], v[34:49]
	s_waitcnt vmcnt(6)
	s_barrier
	ds_read_b128 v[92:95], v84 offset:32768
	ds_read_b128 v[96:99], v84 offset:36864
	ds_read_b128 v[100:103], v86 offset:32768
	ds_read_b128 v[144:147], v86 offset:36864
	ds_read_b128 v[148:151], v88 offset:32768
	ds_read_b128 v[152:155], v88 offset:36864
	ds_read_b128 v[180:183], v90 offset:32768
	ds_read_b128 v[184:187], v90 offset:36864
	s_waitcnt lgkmcnt(0)
	s_barrier
	v_mfma_f32_32x32x16_bf16 v[104:119], v[92:95], v[188:191], v[104:119]
	s_mov_b32 m0, s6
	v_lshl_add_u64 v[82:83], v[66:67], 0, s[26:27]
	v_mfma_f32_32x32x16_bf16 v[128:143], v[92:95], v[192:195], v[128:143]
	global_load_lds_dwordx4 v[82:83], off
	v_lshl_add_u64 v[66:67], v[66:67], 0, s[34:35]
	v_mfma_f32_32x32x16_bf16 v[196:211], v[96:99], v[188:191], v[196:211]
	s_mov_b32 m0, s13
	v_lshl_add_u64 v[82:83], v[70:71], 0, s[26:27]
	v_mfma_f32_32x32x16_bf16 v[236:251], v[96:99], v[192:195], v[236:251]
	global_load_lds_dwordx4 v[82:83], off
	v_lshl_add_u64 v[70:71], v[70:71], 0, s[34:35]
	v_mfma_f32_32x32x16_bf16 v[104:119], v[100:103], v[212:215], v[104:119]
	v_mfma_f32_32x32x16_bf16 v[128:143], v[100:103], v[216:219], v[128:143]
	s_mov_b32 m0, s15
	v_lshl_add_u64 v[82:83], v[74:75], 0, s[26:27]
	v_mfma_f32_32x32x16_bf16 v[196:211], v[144:147], v[212:215], v[196:211]
	global_load_lds_dwordx4 v[82:83], off
	v_lshl_add_u64 v[74:75], v[74:75], 0, s[34:35]
	v_mfma_f32_32x32x16_bf16 v[236:251], v[144:147], v[216:219], v[236:251]
	v_mfma_f32_32x32x16_bf16 v[104:119], v[148:151], v[220:223], v[104:119]
	s_mov_b32 m0, s17
	v_lshl_add_u64 v[82:83], v[78:79], 0, s[26:27]
	v_mfma_f32_32x32x16_bf16 v[128:143], v[148:151], v[224:227], v[128:143]
	global_load_lds_dwordx4 v[82:83], off
	v_lshl_add_u64 v[78:79], v[78:79], 0, s[34:35]
	v_mfma_f32_32x32x16_bf16 v[196:211], v[152:155], v[220:223], v[196:211]
	s_mov_b32 m0, s16
	v_mfma_f32_32x32x16_bf16 v[236:251], v[152:155], v[224:227], v[236:251]
	global_load_lds_dwordx4 v[76:77], off
	v_lshl_add_u64 v[76:77], v[76:77], 0, s[34:35]
	v_mfma_f32_32x32x16_bf16 v[104:119], v[180:183], v[228:231], v[104:119]
	v_mfma_f32_32x32x16_bf16 v[128:143], v[180:183], v[252:255], v[128:143]
	s_mov_b32 m0, s25
	v_mfma_f32_32x32x16_bf16 v[196:211], v[184:187], v[228:231], v[196:211]
	global_load_lds_dwordx4 v[80:81], off
	v_lshl_add_u64 v[80:81], v[80:81], 0, s[34:35]
	v_mfma_f32_32x32x16_bf16 v[236:251], v[184:187], v[252:255], v[236:251]
	s_waitcnt vmcnt(6)
	s_barrier
	s_add_i32 s12, s12, 2
	s_cmp_lt_u32 s12, 14
	s_cbranch_scc1 .Lg1_loop_w1
	ds_read_b128 v[92:95], v84 offset:0
	ds_read_b128 v[96:99], v84 offset:4096
	ds_read_b128 v[188:191], v85 offset:0
	ds_read_b128 v[192:195], v85 offset:4096
	ds_read_b128 v[100:103], v86 offset:0
	ds_read_b128 v[144:147], v86 offset:4096
	ds_read_b128 v[212:215], v87 offset:0
	ds_read_b128 v[216:219], v87 offset:4096
	ds_read_b128 v[148:151], v88 offset:0
	ds_read_b128 v[152:155], v88 offset:4096
	ds_read_b128 v[220:223], v89 offset:0
	ds_read_b128 v[224:227], v89 offset:4096
	ds_read_b128 v[180:183], v90 offset:0
	ds_read_b128 v[184:187], v90 offset:4096
	ds_read_b128 v[228:231], v91 offset:0
	ds_read_b128 v[252:255], v91 offset:4096
	s_waitcnt lgkmcnt(0)
	s_barrier
	v_mfma_f32_32x32x16_bf16 v[18:33], v[92:95], v[188:191], v[18:33]
	s_mov_b32 m0, s1
	v_mfma_f32_32x32x16_bf16 v[50:65], v[92:95], v[192:195], v[50:65]
	global_load_lds_dwordx4 v[66:67], off
	v_mfma_f32_32x32x16_bf16 v[2:17], v[96:99], v[188:191], v[2:17]
	s_add_i32 m0, s1, 0x400
	v_mfma_f32_32x32x16_bf16 v[34:49], v[96:99], v[192:195], v[34:49]
	global_load_lds_dwordx4 v[70:71], off
	v_mfma_f32_32x32x16_bf16 v[18:33], v[100:103], v[212:215], v[18:33]
	v_mfma_f32_32x32x16_bf16 v[50:65], v[100:103], v[216:219], v[50:65]
	v_mfma_f32_32x32x16_bf16 v[2:17], v[144:147], v[212:215], v[2:17]
	v_mfma_f32_32x32x16_bf16 v[34:49], v[144:147], v[216:219], v[34:49]
	v_mfma_f32_32x32x16_bf16 v[18:33], v[148:151], v[220:223], v[18:33]
	s_add_i32 m0, s1, 0x800
	v_mfma_f32_32x32x16_bf16 v[50:65], v[148:151], v[224:227], v[50:65]
	global_load_lds_dwordx4 v[74:75], off
	v_mfma_f32_32x32x16_bf16 v[2:17], v[152:155], v[220:223], v[2:17]
	s_add_i32 m0, s1, 0xc00
	v_mfma_f32_32x32x16_bf16 v[34:49], v[152:155], v[224:227], v[34:49]
	global_load_lds_dwordx4 v[78:79], off
	v_mfma_f32_32x32x16_bf16 v[18:33], v[180:183], v[228:231], v[18:33]
	v_mfma_f32_32x32x16_bf16 v[50:65], v[180:183], v[252:255], v[50:65]
	v_mfma_f32_32x32x16_bf16 v[2:17], v[184:187], v[228:231], v[2:17]
	v_mfma_f32_32x32x16_bf16 v[34:49], v[184:187], v[252:255], v[34:49]
	s_waitcnt vmcnt(4)
	s_barrier
	ds_read_b128 v[92:95], v84 offset:32768
	ds_read_b128 v[96:99], v84 offset:36864
	ds_read_b128 v[100:103], v86 offset:32768
	ds_read_b128 v[144:147], v86 offset:36864
	ds_read_b128 v[148:151], v88 offset:32768
	ds_read_b128 v[152:155], v88 offset:36864
	ds_read_b128 v[180:183], v90 offset:32768
	ds_read_b128 v[184:187], v90 offset:36864
	s_waitcnt lgkmcnt(0)
	s_barrier
	v_mfma_f32_32x32x16_bf16 v[104:119], v[92:95], v[188:191], v[104:119]
	s_mov_b32 m0, s6
	v_lshl_add_u64 v[82:83], v[66:67], 0, s[26:27]
	v_mfma_f32_32x32x16_bf16 v[128:143], v[92:95], v[192:195], v[128:143]
	global_load_lds_dwordx4 v[82:83], off
	v_lshl_add_u64 v[66:67], v[66:67], 0, s[34:35]
	v_mfma_f32_32x32x16_bf16 v[196:211], v[96:99], v[188:191], v[196:211]
	s_mov_b32 m0, s13
	v_lshl_add_u64 v[82:83], v[70:71], 0, s[26:27]
	v_mfma_f32_32x32x16_bf16 v[236:251], v[96:99], v[192:195], v[236:251]
	global_load_lds_dwordx4 v[82:83], off
	v_lshl_add_u64 v[70:71], v[70:71], 0, s[34:35]
	v_mfma_f32_32x32x16_bf16 v[104:119], v[100:103], v[212:215], v[104:119]
	v_mfma_f32_32x32x16_bf16 v[128:143], v[100:103], v[216:219], v[128:143]
	v_mfma_f32_32x32x16_bf16 v[196:211], v[144:147], v[212:215], v[196:211]
	v_mfma_f32_32x32x16_bf16 v[236:251], v[144:147], v[216:219], v[236:251]
	v_mfma_f32_32x32x16_bf16 v[104:119], v[148:151], v[220:223], v[104:119]
	s_mov_b32 m0, s15
	v_lshl_add_u64 v[82:83], v[74:75], 0, s[26:27]
	v_mfma_f32_32x32x16_bf16 v[128:143], v[148:151], v[224:227], v[128:143]
	global_load_lds_dwordx4 v[82:83], off
	v_lshl_add_u64 v[74:75], v[74:75], 0, s[34:35]
	v_mfma_f32_32x32x16_bf16 v[196:211], v[152:155], v[220:223], v[196:211]
	s_mov_b32 m0, s17
	v_lshl_add_u64 v[82:83], v[78:79], 0, s[26:27]
	v_mfma_f32_32x32x16_bf16 v[236:251], v[152:155], v[224:227], v[236:251]
	global_load_lds_dwordx4 v[82:83], off
	v_lshl_add_u64 v[78:79], v[78:79], 0, s[34:35]
	v_mfma_f32_32x32x16_bf16 v[104:119], v[180:183], v[228:231], v[104:119]
	v_mfma_f32_32x32x16_bf16 v[128:143], v[180:183], v[252:255], v[128:143]
	v_mfma_f32_32x32x16_bf16 v[196:211], v[184:187], v[228:231], v[196:211]
	v_mfma_f32_32x32x16_bf16 v[236:251], v[184:187], v[252:255], v[236:251]
	s_waitcnt vmcnt(4)
	s_barrier
	ds_read_b128 v[92:95], v84 offset:0
	ds_read_b128 v[96:99], v84 offset:4096
	ds_read_b128 v[188:191], v85 offset:32768
	ds_read_b128 v[192:195], v85 offset:36864
	ds_read_b128 v[100:103], v86 offset:0
	ds_read_b128 v[144:147], v86 offset:4096
	ds_read_b128 v[212:215], v87 offset:32768
	ds_read_b128 v[216:219], v87 offset:36864
	ds_read_b128 v[148:151], v88 offset:0
	ds_read_b128 v[152:155], v88 offset:4096
	ds_read_b128 v[220:223], v89 offset:32768
	ds_read_b128 v[224:227], v89 offset:36864
	ds_read_b128 v[180:183], v90 offset:0
	ds_read_b128 v[184:187], v90 offset:4096
	ds_read_b128 v[228:231], v91 offset:32768
	ds_read_b128 v[252:255], v91 offset:36864
	s_waitcnt lgkmcnt(0)
	s_barrier
	v_mfma_f32_32x32x16_bf16 v[18:33], v[92:95], v[188:191], v[18:33]
	v_mfma_f32_32x32x16_bf16 v[50:65], v[92:95], v[192:195], v[50:65]
	v_mfma_f32_32x32x16_bf16 v[2:17], v[96:99], v[188:191], v[2:17]
	v_mfma_f32_32x32x16_bf16 v[34:49], v[96:99], v[192:195], v[34:49]
	v_mfma_f32_32x32x16_bf16 v[18:33], v[100:103], v[212:215], v[18:33]
	v_mfma_f32_32x32x16_bf16 v[50:65], v[100:103], v[216:219], v[50:65]
	v_mfma_f32_32x32x16_bf16 v[2:17], v[144:147], v[212:215], v[2:17]
	v_mfma_f32_32x32x16_bf16 v[34:49], v[144:147], v[216:219], v[34:49]
	v_mfma_f32_32x32x16_bf16 v[18:33], v[148:151], v[220:223], v[18:33]
	v_mfma_f32_32x32x16_bf16 v[50:65], v[148:151], v[224:227], v[50:65]
	v_mfma_f32_32x32x16_bf16 v[2:17], v[152:155], v[220:223], v[2:17]
	v_mfma_f32_32x32x16_bf16 v[34:49], v[152:155], v[224:227], v[34:49]
	v_mfma_f32_32x32x16_bf16 v[18:33], v[180:183], v[228:231], v[18:33]
	v_mfma_f32_32x32x16_bf16 v[50:65], v[180:183], v[252:255], v[50:65]
	v_mfma_f32_32x32x16_bf16 v[2:17], v[184:187], v[228:231], v[2:17]
	v_mfma_f32_32x32x16_bf16 v[34:49], v[184:187], v[252:255], v[34:49]
	s_waitcnt vmcnt(0)
	s_barrier
	ds_read_b128 v[92:95], v84 offset:32768
	ds_read_b128 v[96:99], v84 offset:36864
	ds_read_b128 v[100:103], v86 offset:32768
	ds_read_b128 v[144:147], v86 offset:36864
	ds_read_b128 v[148:151], v88 offset:32768
	ds_read_b128 v[152:155], v88 offset:36864
	ds_read_b128 v[180:183], v90 offset:32768
	ds_read_b128 v[184:187], v90 offset:36864
	s_waitcnt lgkmcnt(0)
	s_barrier
	v_mfma_f32_32x32x16_bf16 v[104:119], v[92:95], v[188:191], v[104:119]
	v_mfma_f32_32x32x16_bf16 v[128:143], v[92:95], v[192:195], v[128:143]
	v_mfma_f32_32x32x16_bf16 v[196:211], v[96:99], v[188:191], v[196:211]
	v_mfma_f32_32x32x16_bf16 v[236:251], v[96:99], v[192:195], v[236:251]
	v_mfma_f32_32x32x16_bf16 v[104:119], v[100:103], v[212:215], v[104:119]
	v_mfma_f32_32x32x16_bf16 v[128:143], v[100:103], v[216:219], v[128:143]
	v_mfma_f32_32x32x16_bf16 v[196:211], v[144:147], v[212:215], v[196:211]
	v_mfma_f32_32x32x16_bf16 v[236:251], v[144:147], v[216:219], v[236:251]
	v_mfma_f32_32x32x16_bf16 v[104:119], v[148:151], v[220:223], v[104:119]
	v_mfma_f32_32x32x16_bf16 v[128:143], v[148:151], v[224:227], v[128:143]
	v_mfma_f32_32x32x16_bf16 v[196:211], v[152:155], v[220:223], v[196:211]
	v_mfma_f32_32x32x16_bf16 v[236:251], v[152:155], v[224:227], v[236:251]
	v_mfma_f32_32x32x16_bf16 v[104:119], v[180:183], v[228:231], v[104:119]
	v_mfma_f32_32x32x16_bf16 v[128:143], v[180:183], v[252:255], v[128:143]
	v_mfma_f32_32x32x16_bf16 v[196:211], v[184:187], v[228:231], v[196:211]
	v_mfma_f32_32x32x16_bf16 v[236:251], v[184:187], v[252:255], v[236:251]
	s_waitcnt vmcnt(0) lgkmcnt(0)
	s_barrier
	s_branch .LBB0_187
.Lg1_loop_w2:
	ds_read_b128 v[92:95], v84 offset:0
	ds_read_b128 v[96:99], v84 offset:4096
	ds_read_b128 v[188:191], v85 offset:0
	ds_read_b128 v[192:195], v85 offset:4096
	ds_read_b128 v[100:103], v86 offset:0
	ds_read_b128 v[144:147], v86 offset:4096
	ds_read_b128 v[212:215], v87 offset:0
	ds_read_b128 v[216:219], v87 offset:4096
	ds_read_b128 v[148:151], v88 offset:0
	ds_read_b128 v[152:155], v88 offset:4096
	ds_read_b128 v[220:223], v89 offset:0
	ds_read_b128 v[224:227], v89 offset:4096
	ds_read_b128 v[180:183], v90 offset:0
	ds_read_b128 v[184:187], v90 offset:4096
	ds_read_b128 v[228:231], v91 offset:0
	ds_read_b128 v[252:255], v91 offset:4096
	s_waitcnt lgkmcnt(0)
	s_barrier
	v_mfma_f32_32x32x16_bf16 v[18:33], v[92:95], v[188:191], v[18:33]
	s_mov_b32 m0, s1
	v_mfma_f32_32x32x16_bf16 v[50:65], v[92:95], v[192:195], v[50:65]
	global_load_lds_dwordx4 v[66:67], off
	v_mfma_f32_32x32x16_bf16 v[2:17], v[96:99], v[188:191], v[2:17]
	v_mfma_f32_32x32x16_bf16 v[34:49], v[96:99], v[192:195], v[34:49]
	s_add_i32 m0, s1, 0x400
	v_mfma_f32_32x32x16_bf16 v[18:33], v[100:103], v[212:215], v[18:33]
	global_load_lds_dwordx4 v[70:71], off
	v_mfma_f32_32x32x16_bf16 v[50:65], v[100:103], v[216:219], v[50:65]
	v_mfma_f32_32x32x16_bf16 v[2:17], v[144:147], v[212:215], v[2:17]
	s_add_i32 m0, s1, 0x800
	v_mfma_f32_32x32x16_bf16 v[34:49], v[144:147], v[216:219], v[34:49]
	global_load_lds_dwordx4 v[74:75], off
	v_mfma_f32_32x32x16_bf16 v[18:33], v[148:151], v[220:223], v[18:33]
	s_add_i32 m0, s1, 0xc00
	v_mfma_f32_32x32x16_bf16 v[50:65], v[148:151], v[224:227], v[50:65]
	global_load_lds_dwordx4 v[78:79], off
	v_mfma_f32_32x32x16_bf16 v[2:17], v[152:155], v[220:223], v[2:17]
	v_mfma_f32_32x32x16_bf16 v[34:49], v[152:155], v[224:227], v[34:49]
	s_mov_b32 m0, s8
	v_mfma_f32_32x32x16_bf16 v[18:33], v[180:183], v[228:231], v[18:33]
	global_load_lds_dwordx4 v[68:69], off
	v_lshl_add_u64 v[68:69], v[68:69], 0, s[34:35]
	v_mfma_f32_32x32x16_bf16 v[50:65], v[180:183], v[252:255], v[50:65]
	v_mfma_f32_32x32x16_bf16 v[2:17], v[184:187], v[228:231], v[2:17]
	s_mov_b32 m0, s9
	v_mfma_f32_32x32x16_bf16 v[34:49], v[184:187], v[252:255], v[34:49]
	global_load_lds_dwordx4 v[72:73], off
	v_lshl_add_u64 v[72:73], v[72:73], 0, s[34:35]
	s_waitcnt vmcnt(6)
	s_barrier
	ds_read_b128 v[92:95], v84 offset:32768
	ds_read_b128 v[96:99], v84 offset:36864
	ds_read_b128 v[100:103], v86 offset:32768
	ds_read_b128 v[144:147], v86 offset:36864
	ds_read_b128 v[148:151], v88 offset:32768
	ds_read_b128 v[152:155], v88 offset:36864
	ds_read_b128 v[180:183], v90 offset:32768
	ds_read_b128 v[184:187], v90 offset:36864
	s_waitcnt lgkmcnt(0)
	s_barrier
	v_mfma_f32_32x32x16_bf16 v[104:119], v[92:95], v[188:191], v[104:119]
	s_mov_b32 m0, s6
	v_lshl_add_u64 v[82:83], v[66:67], 0, s[26:27]
	v_mfma_f32_32x32x16_bf16 v[128:143], v[92:95], v[192:195], v[128:143]
	global_load_lds_dwordx4 v[82:83], off
	v_lshl_add_u64 v[66:67], v[66:67], 0, s[34:35]
	v_mfma_f32_32x32x16_bf16 v[196:211], v[96:99], v[188:191], v[196:211]
	v_mfma_f32_32x32x16_bf16 v[236:251], v[96:99], v[192:195], v[236:251]
	s_mov_b32 m0, s13
	v_lshl_add_u64 v[82:83], v[70:71], 0, s[26:27]
	v_mfma_f32_32x32x16_bf16 v[104:119], v[100:103], v[212:215], v[104:119]
	global_load_lds_dwordx4 v[82:83], off
	v_lshl_add_u64 v[70:71], v[70:71], 0, s[34:35]
	v_mfma_f32_32x32x16_bf16 v[128:143], v[100:103], v[216:219], v[128:143]
	v_mfma_f32_32x32x16_bf16 v[196:211], v[144:147], v[212:215], v[196:211]
	s_mov_b32 m0, s15
	v_lshl_add_u64 v[82:83], v[74:75], 0, s[26:27]
	v_mfma_f32_32x32x16_bf16 v[236:251], v[144:147], v[216:219], v[236:251]
	global_load_lds_dwordx4 v[82:83], off
	v_lshl_add_u64 v[74:75], v[74:75], 0, s[34:35]
	v_mfma_f32_32x32x16_bf16 v[104:119], v[148:151], v[220:223], v[104:119]
	s_mov_b32 m0, s17
	v_lshl_add_u64 v[82:83], v[78:79], 0, s[26:27]
	v_mfma_f32_32x32x16_bf16 v[128:143], v[148:151], v[224:227], v[128:143]
	global_load_lds_dwordx4 v[82:83], off
	v_lshl_add_u64 v[78:79], v[78:79], 0, s[34:35]
	v_mfma_f32_32x32x16_bf16 v[196:211], v[152:155], v[220:223], v[196:211]
	v_mfma_f32_32x32x16_bf16 v[236:251], v[152:155], v[224:227], v[236:251]
	s_mov_b32 m0, s10
	v_mfma_f32_32x32x16_bf16 v[104:119], v[180:183], v[228:231], v[104:119]
	global_load_lds_dwordx4 v[76:77], off
	v_lshl_add_u64 v[76:77], v[76:77], 0, s[34:35]
	v_mfma_f32_32x32x16_bf16 v[128:143], v[180:183], v[252:255], v[128:143]
	v_mfma_f32_32x32x16_bf16 v[196:211], v[184:187], v[228:231], v[196:211]
	s_mov_b32 m0, s11
	v_mfma_f32_32x32x16_bf16 v[236:251], v[184:187], v[252:255], v[236:251]
	global_load_lds_dwordx4 v[80:81], off
	v_lshl_add_u64 v[80:81], v[80:81], 0, s[34:35]
	s_waitcnt vmcnt(6)
	s_barrier
	ds_read_b128 v[92:95], v84 offset:0
	ds_read_b128 v[96:99], v84 offset:4096
	ds_read_b128 v[188:191], v85 offset:32768
	ds_read_b128 v[192:195], v85 offset:36864
	ds_read_b128 v[100:103], v86 offset:0
	ds_read_b128 v[144:147], v86 offset:4096
	ds_read_b128 v[212:215], v87 offset:32768
	ds_read_b128 v[216:219], v87 offset:36864
	ds_read_b128 v[148:151], v88 offset:0
	ds_read_b128 v[152:155], v88 offset:4096
	ds_read_b128 v[220:223], v89 offset:32768
	ds_read_b128 v[224:227], v89 offset:36864
	ds_read_b128 v[180:183], v90 offset:0
	ds_read_b128 v[184:187], v90 offset:4096
	ds_read_b128 v[228:231], v91 offset:32768
	ds_read_b128 v[252:255], v91 offset:36864
	s_waitcnt lgkmcnt(0)
	s_barrier
	v_mfma_f32_32x32x16_bf16 v[18:33], v[92:95], v[188:191], v[18:33]
	s_mov_b32 m0, s1
	v_mfma_f32_32x32x16_bf16 v[50:65], v[92:95], v[192:195], v[50:65]
	global_load_lds_dwordx4 v[66:67], off
	v_mfma_f32_32x32x16_bf16 v[2:17], v[96:99], v[188:191], v[2:17]
	v_mfma_f32_32x32x16_bf16 v[34:49], v[96:99], v[192:195], v[34:49]
	s_add_i32 m0, s1, 0x400
	v_mfma_f32_32x32x16_bf16 v[18:33], v[100:103], v[212:215], v[18:33]
	global_load_lds_dwordx4 v[70:71], off
	v_mfma_f32_32x32x16_bf16 v[50:65], v[100:103], v[216:219], v[50:65]
	v_mfma_f32_32x32x16_bf16 v[2:17], v[144:147], v[212:215], v[2:17]
	s_add_i32 m0, s1, 0x800
	v_mfma_f32_32x32x16_bf16 v[34:49], v[144:147], v[216:219], v[34:49]
	global_load_lds_dwordx4 v[74:75], off
	v_mfma_f32_32x32x16_bf16 v[18:33], v[148:151], v[220:223], v[18:33]
	s_add_i32 m0, s1, 0xc00
	v_mfma_f32_32x32x16_bf16 v[50:65], v[148:151], v[224:227], v[50:65]
	global_load_lds_dwordx4 v[78:79], off
	v_mfma_f32_32x32x16_bf16 v[2:17], v[152:155], v[220:223], v[2:17]
	v_mfma_f32_32x32x16_bf16 v[34:49], v[152:155], v[224:227], v[34:49]
	s_mov_b32 m0, s7
	v_mfma_f32_32x32x16_bf16 v[18:33], v[180:183], v[228:231], v[18:33]
	global_load_lds_dwordx4 v[68:69], off
	v_lshl_add_u64 v[68:69], v[68:69], 0, s[34:35]
	v_mfma_f32_32x32x16_bf16 v[50:65], v[180:183], v[252:255], v[50:65]
	v_mfma_f32_32x32x16_bf16 v[2:17], v[184:187], v[228:231], v[2:17]
	s_mov_b32 m0, s14
	v_mfma_f32_32x32x16_bf16 v[34:49], v[184:187], v[252:255], v[34:49]
	global_load_lds_dwordx4 v[72:73], off
	v_lshl_add_u64 v[72:73], v[72:73], 0, s[34:35]
	s_waitcnt vmcnt(6)
	s_barrier
	ds_read_b128 v[92:95], v84 offset:32768
	ds_read_b128 v[96:99], v84 offset:36864
	ds_read_b128 v[100:103], v86 offset:32768
	ds_read_b128 v[144:147], v86 offset:36864
	ds_read_b128 v[148:151], v88 offset:32768
	ds_read_b128 v[152:155], v88 offset:36864
	ds_read_b128 v[180:183], v90 offset:32768
	ds_read_b128 v[184:187], v90 offset:36864
	s_waitcnt lgkmcnt(0)
	s_barrier
	v_mfma_f32_32x32x16_bf16 v[104:119], v[92:95], v[188:191], v[104:119]
	s_mov_b32 m0, s6
	v_lshl_add_u64 v[82:83], v[66:67], 0, s[26:27]
	v_mfma_f32_32x32x16_bf16 v[128:143], v[92:95], v[192:195], v[128:143]
	global_load_lds_dwordx4 v[82:83], off
	v_lshl_add_u64 v[66:67], v[66:67], 0, s[34:35]
	v_mfma_f32_32x32x16_bf16 v[196:211], v[96:99], v[188:191], v[196:211]
	v_mfma_f32_32x32x16_bf16 v[236:251], v[96:99], v[192:195], v[236:251]
	s_mov_b32 m0, s13
	v_lshl_add_u64 v[82:83], v[70:71], 0, s[26:27]
	v_mfma_f32_32x32x16_bf16 v[104:119], v[100:103], v[212:215], v[104:119]
	global_load_lds_dwordx4 v[82:83], off
	v_lshl_add_u64 v[70:71], v[70:71], 0, s[34:35]
	v_mfma_f32_32x32x16_bf16 v[128:143], v[100:103], v[216:219], v[128:143]
	v_mfma_f32_32x32x16_bf16 v[196:211], v[144:147], v[212:215], v[196:211]
	s_mov_b32 m0, s15
	v_lshl_add_u64 v[82:83], v[74:75], 0, s[26:27]
	v_mfma_f32_32x32x16_bf16 v[236:251], v[144:147], v[216:219], v[236:251]
	global_load_lds_dwordx4 v[82:83], off
	v_lshl_add_u64 v[74:75], v[74:75], 0, s[34:35]
	v_mfma_f32_32x32x16_bf16 v[104:119], v[148:151], v[220:223], v[104:119]
	s_mov_b32 m0, s17
	v_lshl_add_u64 v[82:83], v[78:79], 0, s[26:27]
	v_mfma_f32_32x32x16_bf16 v[128:143], v[148:151], v[224:227], v[128:143]
	global_load_lds_dwordx4 v[82:83], off
	v_lshl_add_u64 v[78:79], v[78:79], 0, s[34:35]
	v_mfma_f32_32x32x16_bf16 v[196:211], v[152:155], v[220:223], v[196:211]
	v_mfma_f32_32x32x16_bf16 v[236:251], v[152:155], v[224:227], v[236:251]
	s_mov_b32 m0, s16
	v_mfma_f32_32x32x16_bf16 v[104:119], v[180:183], v[228:231], v[104:119]
	global_load_lds_dwordx4 v[76:77], off
	v_lshl_add_u64 v[76:77], v[76:77], 0, s[34:35]
	v_mfma_f32_32x32x16_bf16 v[128:143], v[180:183], v[252:255], v[128:143]
	v_mfma_f32_32x32x16_bf16 v[196:211], v[184:187], v[228:231], v[196:211]
	s_mov_b32 m0, s25
	v_mfma_f32_32x32x16_bf16 v[236:251], v[184:187], v[252:255], v[236:251]
	global_load_lds_dwordx4 v[80:81], off
	v_lshl_add_u64 v[80:81], v[80:81], 0, s[34:35]
	s_waitcnt vmcnt(6)
	s_barrier
	s_add_i32 s12, s12, 2
	s_cmp_lt_u32 s12, 14
	s_cbranch_scc1 .Lg1_loop_w2
	ds_read_b128 v[92:95], v84 offset:0
	ds_read_b128 v[96:99], v84 offset:4096
	ds_read_b128 v[188:191], v85 offset:0
	ds_read_b128 v[192:195], v85 offset:4096
	ds_read_b128 v[100:103], v86 offset:0
	ds_read_b128 v[144:147], v86 offset:4096
	ds_read_b128 v[212:215], v87 offset:0
	ds_read_b128 v[216:219], v87 offset:4096
	ds_read_b128 v[148:151], v88 offset:0
	ds_read_b128 v[152:155], v88 offset:4096
	ds_read_b128 v[220:223], v89 offset:0
	ds_read_b128 v[224:227], v89 offset:4096
	ds_read_b128 v[180:183], v90 offset:0
	ds_read_b128 v[184:187], v90 offset:4096
	ds_read_b128 v[228:231], v91 offset:0
	ds_read_b128 v[252:255], v91 offset:4096
	s_waitcnt lgkmcnt(0)
	s_barrier
	v_mfma_f32_32x32x16_bf16 v[18:33], v[92:95], v[188:191], v[18:33]
	s_mov_b32 m0, s1
	v_mfma_f32_32x32x16_bf16 v[50:65], v[92:95], v[192:195], v[50:65]
	global_load_lds_dwordx4 v[66:67], off
	v_mfma_f32_32x32x16_bf16 v[2:17], v[96:99], v[188:191], v[2:17]
	v_mfma_f32_32x32x16_bf16 v[34:49], v[96:99], v[192:195], v[34:49]
	s_add_i32 m0, s1, 0x400
	v_mfma_f32_32x32x16_bf16 v[18:33], v[100:103], v[212:215], v[18:33]
	global_load_lds_dwordx4 v[70:71], off
	v_mfma_f32_32x32x16_bf16 v[50:65], v[100:103], v[216:219], v[50:65]
	v_mfma_f32_32x32x16_bf16 v[2:17], v[144:147], v[212:215], v[2:17]
	v_mfma_f32_32x32x16_bf16 v[34:49], v[144:147], v[216:219], v[34:49]
	v_mfma_f32_32x32x16_bf16 v[18:33], v[148:151], v[220:223], v[18:33]
	s_add_i32 m0, s1, 0x800
	v_mfma_f32_32x32x16_bf16 v[50:65], v[148:151], v[224:227], v[50:65]
	global_load_lds_dwordx4 v[74:75], off
	v_mfma_f32_32x32x16_bf16 v[2:17], v[152:155], v[220:223], v[2:17]
	v_mfma_f32_32x32x16_bf16 v[34:49], v[152:155], v[224:227], v[34:49]
	s_add_i32 m0, s1, 0xc00
	v_mfma_f32_32x32x16_bf16 v[18:33], v[180:183], v[228:231], v[18:33]
	global_load_lds_dwordx4 v[78:79], off
	v_mfma_f32_32x32x16_bf16 v[50:65], v[180:183], v[252:255], v[50:65]
	v_mfma_f32_32x32x16_bf16 v[2:17], v[184:187], v[228:231], v[2:17]
	v_mfma_f32_32x32x16_bf16 v[34:49], v[184:187], v[252:255], v[34:49]
	s_waitcnt vmcnt(4)
	s_barrier
	ds_read_b128 v[92:95], v84 offset:32768
	ds_read_b128 v[96:99], v84 offset:36864
	ds_read_b128 v[100:103], v86 offset:32768
	ds_read_b128 v[144:147], v86 offset:36864
	ds_read_b128 v[148:151], v88 offset:32768
	ds_read_b128 v[152:155], v88 offset:36864
	ds_read_b128 v[180:183], v90 offset:32768
	ds_read_b128 v[184:187], v90 offset:36864
	s_waitcnt lgkmcnt(0)
	s_barrier
	v_mfma_f32_32x32x16_bf16 v[104:119], v[92:95], v[188:191], v[104:119]
	s_mov_b32 m0, s6
	v_lshl_add_u64 v[82:83], v[66:67], 0, s[26:27]
	v_mfma_f32_32x32x16_bf16 v[128:143], v[92:95], v[192:195], v[128:143]
	global_load_lds_dwordx4 v[82:83], off
	v_lshl_add_u64 v[66:67], v[66:67], 0, s[34:35]
	v_mfma_f32_32x32x16_bf16 v[196:211], v[96:99], v[188:191], v[196:211]
	v_mfma_f32_32x32x16_bf16 v[236:251], v[96:99], v[192:195], v[236:251]
	s_mov_b32 m0, s13
	v_lshl_add_u64 v[82:83], v[70:71], 0, s[26:27]
	v_mfma_f32_32x32x16_bf16 v[104:119], v[100:103], v[212:215], v[104:119]
	global_load_lds_dwordx4 v[82:83], off
	v_lshl_add_u64 v[70:71], v[70:71], 0, s[34:35]
	v_mfma_f32_32x32x16_bf16 v[128:143], v[100:103], v[216:219], v[128:143]
	v_mfma_f32_32x32x16_bf16 v[196:211], v[144:147], v[212:215], v[196:211]
	v_mfma_f32_32x32x16_bf16 v[236:251], v[144:147], v[216:219], v[236:251]
	v_mfma_f32_32x32x16_bf16 v[104:119], v[148:151], v[220:223], v[104:119]
	s_mov_b32 m0, s15
	v_lshl_add_u64 v[82:83], v[74:75], 0, s[26:27]
	v_mfma_f32_32x32x16_bf16 v[128:143], v[148:151], v[224:227], v[128:143]
	global_load_lds_dwordx4 v[82:83], off
	v_lshl_add_u64 v[74:75], v[74:75], 0, s[34:35]
	v_mfma_f32_32x32x16_bf16 v[196:211], v[152:155], v[220:223], v[196:211]
	v_mfma_f32_32x32x16_bf16 v[236:251], v[152:155], v[224:227], v[236:251]
	s_mov_b32 m0, s17
	v_lshl_add_u64 v[82:83], v[78:79], 0, s[26:27]
	v_mfma_f32_32x32x16_bf16 v[104:119], v[180:183], v[228:231], v[104:119]
	global_load_lds_dwordx4 v[82:83], off
	v_lshl_add_u64 v[78:79], v[78:79], 0, s[34:35]
	v_mfma_f32_32x32x16_bf16 v[128:143], v[180:183], v[252:255], v[128:143]
	v_mfma_f32_32x32x16_bf16 v[196:211], v[184:187], v[228:231], v[196:211]
	v_mfma_f32_32x32x16_bf16 v[236:251], v[184:187], v[252:255], v[236:251]
	s_waitcnt vmcnt(4)
	s_barrier
	ds_read_b128 v[92:95], v84 offset:0
	ds_read_b128 v[96:99], v84 offset:4096
	ds_read_b128 v[188:191], v85 offset:32768
	ds_read_b128 v[192:195], v85 offset:36864
	ds_read_b128 v[100:103], v86 offset:0
	ds_read_b128 v[144:147], v86 offset:4096
	ds_read_b128 v[212:215], v87 offset:32768
	ds_read_b128 v[216:219], v87 offset:36864
	ds_read_b128 v[148:151], v88 offset:0
	ds_read_b128 v[152:155], v88 offset:4096
	ds_read_b128 v[220:223], v89 offset:32768
	ds_read_b128 v[224:227], v89 offset:36864
	ds_read_b128 v[180:183], v90 offset:0
	ds_read_b128 v[184:187], v90 offset:4096
	ds_read_b128 v[228:231], v91 offset:32768
	ds_read_b128 v[252:255], v91 offset:36864
	s_waitcnt lgkmcnt(0)
	s_barrier
	v_mfma_f32_32x32x16_bf16 v[18:33], v[92:95], v[188:191], v[18:33]
	v_mfma_f32_32x32x16_bf16 v[50:65], v[92:95], v[192:195], v[50:65]
	v_mfma_f32_32x32x16_bf16 v[2:17], v[96:99], v[188:191], v[2:17]
	v_mfma_f32_32x32x16_bf16 v[34:49], v[96:99], v[192:195], v[34:49]
	v_mfma_f32_32x32x16_bf16 v[18:33], v[100:103], v[212:215], v[18:33]
	v_mfma_f32_32x32x16_bf16 v[50:65], v[100:103], v[216:219], v[50:65]
	v_mfma_f32_32x32x16_bf16 v[2:17], v[144:147], v[212:215], v[2:17]
	v_mfma_f32_32x32x16_bf16 v[34:49], v[144:147], v[216:219], v[34:49]
	v_mfma_f32_32x32x16_bf16 v[18:33], v[148:151], v[220:223], v[18:33]
	v_mfma_f32_32x32x16_bf16 v[50:65], v[148:151], v[224:227], v[50:65]
	v_mfma_f32_32x32x16_bf16 v[2:17], v[152:155], v[220:223], v[2:17]
	v_mfma_f32_32x32x16_bf16 v[34:49], v[152:155], v[224:227], v[34:49]
	v_mfma_f32_32x32x16_bf16 v[18:33], v[180:183], v[228:231], v[18:33]
	v_mfma_f32_32x32x16_bf16 v[50:65], v[180:183], v[252:255], v[50:65]
	v_mfma_f32_32x32x16_bf16 v[2:17], v[184:187], v[228:231], v[2:17]
	v_mfma_f32_32x32x16_bf16 v[34:49], v[184:187], v[252:255], v[34:49]
	s_waitcnt vmcnt(0)
	s_barrier
	ds_read_b128 v[92:95], v84 offset:32768
	ds_read_b128 v[96:99], v84 offset:36864
	ds_read_b128 v[100:103], v86 offset:32768
	ds_read_b128 v[144:147], v86 offset:36864
	ds_read_b128 v[148:151], v88 offset:32768
	ds_read_b128 v[152:155], v88 offset:36864
	ds_read_b128 v[180:183], v90 offset:32768
	ds_read_b128 v[184:187], v90 offset:36864
	s_waitcnt lgkmcnt(0)
	s_barrier
	v_mfma_f32_32x32x16_bf16 v[104:119], v[92:95], v[188:191], v[104:119]
	v_mfma_f32_32x32x16_bf16 v[128:143], v[92:95], v[192:195], v[128:143]
	v_mfma_f32_32x32x16_bf16 v[196:211], v[96:99], v[188:191], v[196:211]
	v_mfma_f32_32x32x16_bf16 v[236:251], v[96:99], v[192:195], v[236:251]
	v_mfma_f32_32x32x16_bf16 v[104:119], v[100:103], v[212:215], v[104:119]
	v_mfma_f32_32x32x16_bf16 v[128:143], v[100:103], v[216:219], v[128:143]
	v_mfma_f32_32x32x16_bf16 v[196:211], v[144:147], v[212:215], v[196:211]
	v_mfma_f32_32x32x16_bf16 v[236:251], v[144:147], v[216:219], v[236:251]
	v_mfma_f32_32x32x16_bf16 v[104:119], v[148:151], v[220:223], v[104:119]
	v_mfma_f32_32x32x16_bf16 v[128:143], v[148:151], v[224:227], v[128:143]
	v_mfma_f32_32x32x16_bf16 v[196:211], v[152:155], v[220:223], v[196:211]
	v_mfma_f32_32x32x16_bf16 v[236:251], v[152:155], v[224:227], v[236:251]
	v_mfma_f32_32x32x16_bf16 v[104:119], v[180:183], v[228:231], v[104:119]
	v_mfma_f32_32x32x16_bf16 v[128:143], v[180:183], v[252:255], v[128:143]
	v_mfma_f32_32x32x16_bf16 v[196:211], v[184:187], v[228:231], v[196:211]
	v_mfma_f32_32x32x16_bf16 v[236:251], v[184:187], v[252:255], v[236:251]
	s_waitcnt vmcnt(0) lgkmcnt(0)
	s_barrier
	s_branch .LBB0_187
.Lg1_loop_w3:
	ds_read_b128 v[92:95], v84 offset:0
	ds_read_b128 v[96:99], v84 offset:4096
	ds_read_b128 v[188:191], v85 offset:0
	ds_read_b128 v[192:195], v85 offset:4096
	ds_read_b128 v[100:103], v86 offset:0
	ds_read_b128 v[144:147], v86 offset:4096
	ds_read_b128 v[212:215], v87 offset:0
	ds_read_b128 v[216:219], v87 offset:4096
	ds_read_b128 v[148:151], v88 offset:0
	ds_read_b128 v[152:155], v88 offset:4096
	ds_read_b128 v[220:223], v89 offset:0
	ds_read_b128 v[224:227], v89 offset:4096
	ds_read_b128 v[180:183], v90 offset:0
	ds_read_b128 v[184:187], v90 offset:4096
	ds_read_b128 v[228:231], v91 offset:0
	ds_read_b128 v[252:255], v91 offset:4096
	s_waitcnt lgkmcnt(0)
	s_barrier
	v_mfma_f32_32x32x16_bf16 v[18:33], v[92:95], v[188:191], v[18:33]
	v_mfma_f32_32x32x16_bf16 v[50:65], v[92:95], v[192:195], v[50:65]
	s_mov_b32 m0, s1
	v_mfma_f32_32x32x16_bf16 v[2:17], v[96:99], v[188:191], v[2:17]
	global_load_lds_dwordx4 v[66:67], off
	v_mfma_f32_32x32x16_bf16 v[34:49], v[96:99], v[192:195], v[34:49]
	v_mfma_f32_32x32x16_bf16 v[18:33], v[100:103], v[212:215], v[18:33]
	s_add_i32 m0, s1, 0x400
	v_mfma_f32_32x32x16_bf16 v[50:65], v[100:103], v[216:219], v[50:65]
	global_load_lds_dwordx4 v[70:71], off
	v_mfma_f32_32x32x16_bf16 v[2:17], v[144:147], v[212:215], v[2:17]
	s_add_i32 m0, s1, 0x800
	v_mfma_f32_32x32x16_bf16 v[34:49], v[144:147], v[216:219], v[34:49]
	global_load_lds_dwordx4 v[74:75], off
	v_mfma_f32_32x32x16_bf16 v[18:33], v[148:151], v[220:223], v[18:33]
	v_mfma_f32_32x32x16_bf16 v[50:65], v[148:151], v[224:227], v[50:65]
	s_add_i32 m0, s1, 0xc00
	v_mfma_f32_32x32x16_bf16 v[2:17], v[152:155], v[220:223], v[2:17]
	global_load_lds_dwordx4 v[78:79], off
	v_mfma_f32_32x32x16_bf16 v[34:49], v[152:155], v[224:227], v[34:49]
	v_mfma_f32_32x32x16_bf16 v[18:33], v[180:183], v[228:231], v[18:33]
	s_mov_b32 m0, s8
	v_mfma_f32_32x32x16_bf16 v[50:65], v[180:183], v[252:255], v[50:65]
	global_load_lds_dwordx4 v[68:69], off
	v_lshl_add_u64 v[68:69], v[68:69], 0, s[34:35]
	v_mfma_f32_32x32x16_bf16 v[2:17], v[184:187], v[228:231], v[2:17]
	s_mov_b32 m0, s9
	v_mfma_f32_32x32x16_bf16 v[34:49], v[184:187], v[252:255], v[34:49]
	global_load_lds_dwordx4 v[72:73], off
	v_lshl_add_u64 v[72:73], v[72:73], 0, s[34:35]
	s_waitcnt vmcnt(6)
	s_barrier
	ds_read_b128 v[92:95], v84 offset:32768
	ds_read_b128 v[96:99], v84 offset:36864
	ds_read_b128 v[100:103], v86 offset:32768
	ds_read_b128 v[144:147], v86 offset:36864
	ds_read_b128 v[148:151], v88 offset:32768
	ds_read_b128 v[152:155], v88 offset:36864
	ds_read_b128 v[180:183], v90 offset:32768
	ds_read_b128 v[184:187], v90 offset:36864
	s_waitcnt lgkmcnt(0)
	s_barrier
	v_mfma_f32_32x32x16_bf16 v[104:119], v[92:95], v[188:191], v[104:119]
	v_mfma_f32_32x32x16_bf16 v[128:143], v[92:95], v[192:195], v[128:143]
	s_mov_b32 m0, s6
	v_lshl_add_u64 v[82:83], v[66:67], 0, s[26:27]
	v_mfma_f32_32x32x16_bf16 v[196:211], v[96:99], v[188:191], v[196:211]
	global_load_lds_dwordx4 v[82:83], off
	v_lshl_add_u64 v[66:67], v[66:67], 0, s[34:35]
	v_mfma_f32_32x32x16_bf16 v[236:251], v[96:99], v[192:195], v[236:251]
	v_mfma_f32_32x32x16_bf16 v[104:119], v[100:103], v[212:215], v[104:119]
	s_mov_b32 m0, s13
	v_lshl_add_u64 v[82:83], v[70:71], 0, s[26:27]
	v_mfma_f32_32x32x16_bf16 v[128:143], v[100:103], v[216:219], v[128:143]
	global_load_lds_dwordx4 v[82:83], off
	v_lshl_add_u64 v[70:71], v[70:71], 0, s[34:35]
	v_mfma_f32_32x32x16_bf16 v[196:211], v[144:147], v[212:215], v[196:211]
	s_mov_b32 m0, s15
	v_lshl_add_u64 v[82:83], v[74:75], 0, s[26:27]
	v_mfma_f32_32x32x16_bf16 v[236:251], v[144:147], v[216:219], v[236:251]
	global_load_lds_dwordx4 v[82:83], off
	v_lshl_add_u64 v[74:75], v[74:75], 0, s[34:35]
	v_mfma_f32_32x32x16_bf16 v[104:119], v[148:151], v[220:223], v[104:119]
	v_mfma_f32_32x32x16_bf16 v[128:143], v[148:151], v[224:227], v[128:143]
	s_mov_b32 m0, s17
	v_lshl_add_u64 v[82:83], v[78:79], 0, s[26:27]
	v_mfma_f32_32x32x16_bf16 v[196:211], v[152:155], v[220:223], v[196:211]
	global_load_lds_dwordx4 v[82:83], off
	v_lshl_add_u64 v[78:79], v[78:79], 0, s[34:35]
	v_mfma_f32_32x32x16_bf16 v[236:251], v[152:155], v[224:227], v[236:251]
	v_mfma_f32_32x32x16_bf16 v[104:119], v[180:183], v[228:231], v[104:119]
	s_mov_b32 m0, s10
	v_mfma_f32_32x32x16_bf16 v[128:143], v[180:183], v[252:255], v[128:143]
	global_load_lds_dwordx4 v[76:77], off
	v_lshl_add_u64 v[76:77], v[76:77], 0, s[34:35]
	v_mfma_f32_32x32x16_bf16 v[196:211], v[184:187], v[228:231], v[196:211]
	s_mov_b32 m0, s11
	v_mfma_f32_32x32x16_bf16 v[236:251], v[184:187], v[252:255], v[236:251]
	global_load_lds_dwordx4 v[80:81], off
	v_lshl_add_u64 v[80:81], v[80:81], 0, s[34:35]
	s_waitcnt vmcnt(6)
	s_barrier
	ds_read_b128 v[92:95], v84 offset:0
	ds_read_b128 v[96:99], v84 offset:4096
	ds_read_b128 v[188:191], v85 offset:32768
	ds_read_b128 v[192:195], v85 offset:36864
	ds_read_b128 v[100:103], v86 offset:0
	ds_read_b128 v[144:147], v86 offset:4096
	ds_read_b128 v[212:215], v87 offset:32768
	ds_read_b128 v[216:219], v87 offset:36864
	ds_read_b128 v[148:151], v88 offset:0
	ds_read_b128 v[152:155], v88 offset:4096
	ds_read_b128 v[220:223], v89 offset:32768
	ds_read_b128 v[224:227], v89 offset:36864
	ds_read_b128 v[180:183], v90 offset:0
	ds_read_b128 v[184:187], v90 offset:4096
	ds_read_b128 v[228:231], v91 offset:32768
	ds_read_b128 v[252:255], v91 offset:36864
	s_waitcnt lgkmcnt(0)
	s_barrier
	v_mfma_f32_32x32x16_bf16 v[18:33], v[92:95], v[188:191], v[18:33]
	v_mfma_f32_32x32x16_bf16 v[50:65], v[92:95], v[192:195], v[50:65]
	s_mov_b32 m0, s1
	v_mfma_f32_32x32x16_bf16 v[2:17], v[96:99], v[188:191], v[2:17]
	global_load_lds_dwordx4 v[66:67], off
	v_mfma_f32_32x32x16_bf16 v[34:49], v[96:99], v[192:195], v[34:49]
	v_mfma_f32_32x32x16_bf16 v[18:33], v[100:103], v[212:215], v[18:33]
	s_add_i32 m0, s1, 0x400
	v_mfma_f32_32x32x16_bf16 v[50:65], v[100:103], v[216:219], v[50:65]
	global_load_lds_dwordx4 v[70:71], off
	v_mfma_f32_32x32x16_bf16 v[2:17], v[144:147], v[212:215], v[2:17]
	s_add_i32 m0, s1, 0x800
	v_mfma_f32_32x32x16_bf16 v[34:49], v[144:147], v[216:219], v[34:49]
	global_load_lds_dwordx4 v[74:75], off
	v_mfma_f32_32x32x16_bf16 v[18:33], v[148:151], v[220:223], v[18:33]
	v_mfma_f32_32x32x16_bf16 v[50:65], v[148:151], v[224:227], v[50:65]
	s_add_i32 m0, s1, 0xc00
	v_mfma_f32_32x32x16_bf16 v[2:17], v[152:155], v[220:223], v[2:17]
	global_load_lds_dwordx4 v[78:79], off
	v_mfma_f32_32x32x16_bf16 v[34:49], v[152:155], v[224:227], v[34:49]
	v_mfma_f32_32x32x16_bf16 v[18:33], v[180:183], v[228:231], v[18:33]
	s_mov_b32 m0, s7
	v_mfma_f32_32x32x16_bf16 v[50:65], v[180:183], v[252:255], v[50:65]
	global_load_lds_dwordx4 v[68:69], off
	v_lshl_add_u64 v[68:69], v[68:69], 0, s[34:35]
	v_mfma_f32_32x32x16_bf16 v[2:17], v[184:187], v[228:231], v[2:17]
	s_mov_b32 m0, s14
	v_mfma_f32_32x32x16_bf16 v[34:49], v[184:187], v[252:255], v[34:49]
	global_load_lds_dwordx4 v[72:73], off
	v_lshl_add_u64 v[72:73], v[72:73], 0, s[34:35]
	s_waitcnt vmcnt(6)
	s_barrier
	ds_read_b128 v[92:95], v84 offset:32768
	ds_read_b128 v[96:99], v84 offset:36864
	ds_read_b128 v[100:103], v86 offset:32768
	ds_read_b128 v[144:147], v86 offset:36864
	ds_read_b128 v[148:151], v88 offset:32768
	ds_read_b128 v[152:155], v88 offset:36864
	ds_read_b128 v[180:183], v90 offset:32768
	ds_read_b128 v[184:187], v90 offset:36864
	s_waitcnt lgkmcnt(0)
	s_barrier
	v_mfma_f32_32x32x16_bf16 v[104:119], v[92:95], v[188:191], v[104:119]
	v_mfma_f32_32x32x16_bf16 v[128:143], v[92:95], v[192:195], v[128:143]
	s_mov_b32 m0, s6
	v_lshl_add_u64 v[82:83], v[66:67], 0, s[26:27]
	v_mfma_f32_32x32x16_bf16 v[196:211], v[96:99], v[188:191], v[196:211]
	global_load_lds_dwordx4 v[82:83], off
	v_lshl_add_u64 v[66:67], v[66:67], 0, s[34:35]
	v_mfma_f32_32x32x16_bf16 v[236:251], v[96:99], v[192:195], v[236:251]
	v_mfma_f32_32x32x16_bf16 v[104:119], v[100:103], v[212:215], v[104:119]
	s_mov_b32 m0, s13
	v_lshl_add_u64 v[82:83], v[70:71], 0, s[26:27]
	v_mfma_f32_32x32x16_bf16 v[128:143], v[100:103], v[216:219], v[128:143]
	global_load_lds_dwordx4 v[82:83], off
	v_lshl_add_u64 v[70:71], v[70:71], 0, s[34:35]
	v_mfma_f32_32x32x16_bf16 v[196:211], v[144:147], v[212:215], v[196:211]
	s_mov_b32 m0, s15
	v_lshl_add_u64 v[82:83], v[74:75], 0, s[26:27]
	v_mfma_f32_32x32x16_bf16 v[236:251], v[144:147], v[216:219], v[236:251]
	global_load_lds_dwordx4 v[82:83], off
	v_lshl_add_u64 v[74:75], v[74:75], 0, s[34:35]
	v_mfma_f32_32x32x16_bf16 v[104:119], v[148:151], v[220:223], v[104:119]
	v_mfma_f32_32x32x16_bf16 v[128:143], v[148:151], v[224:227], v[128:143]
	s_mov_b32 m0, s17
	v_lshl_add_u64 v[82:83], v[78:79], 0, s[26:27]
	v_mfma_f32_32x32x16_bf16 v[196:211], v[152:155], v[220:223], v[196:211]
	global_load_lds_dwordx4 v[82:83], off
	v_lshl_add_u64 v[78:79], v[78:79], 0, s[34:35]
	v_mfma_f32_32x32x16_bf16 v[236:251], v[152:155], v[224:227], v[236:251]
	v_mfma_f32_32x32x16_bf16 v[104:119], v[180:183], v[228:231], v[104:119]
	s_mov_b32 m0, s16
	v_mfma_f32_32x32x16_bf16 v[128:143], v[180:183], v[252:255], v[128:143]
	global_load_lds_dwordx4 v[76:77], off
	v_lshl_add_u64 v[76:77], v[76:77], 0, s[34:35]
	v_mfma_f32_32x32x16_bf16 v[196:211], v[184:187], v[228:231], v[196:211]
	s_mov_b32 m0, s25
	v_mfma_f32_32x32x16_bf16 v[236:251], v[184:187], v[252:255], v[236:251]
	global_load_lds_dwordx4 v[80:81], off
	v_lshl_add_u64 v[80:81], v[80:81], 0, s[34:35]
	s_waitcnt vmcnt(6)
	s_barrier
	s_add_i32 s12, s12, 2
	s_cmp_lt_u32 s12, 14
	s_cbranch_scc1 .Lg1_loop_w3
	ds_read_b128 v[92:95], v84 offset:0
	ds_read_b128 v[96:99], v84 offset:4096
	ds_read_b128 v[188:191], v85 offset:0
	ds_read_b128 v[192:195], v85 offset:4096
	ds_read_b128 v[100:103], v86 offset:0
	ds_read_b128 v[144:147], v86 offset:4096
	ds_read_b128 v[212:215], v87 offset:0
	ds_read_b128 v[216:219], v87 offset:4096
	ds_read_b128 v[148:151], v88 offset:0
	ds_read_b128 v[152:155], v88 offset:4096
	ds_read_b128 v[220:223], v89 offset:0
	ds_read_b128 v[224:227], v89 offset:4096
	ds_read_b128 v[180:183], v90 offset:0
	ds_read_b128 v[184:187], v90 offset:4096
	ds_read_b128 v[228:231], v91 offset:0
	ds_read_b128 v[252:255], v91 offset:4096
	s_waitcnt lgkmcnt(0)
	s_barrier
	v_mfma_f32_32x32x16_bf16 v[18:33], v[92:95], v[188:191], v[18:33]
	v_mfma_f32_32x32x16_bf16 v[50:65], v[92:95], v[192:195], v[50:65]
	s_mov_b32 m0, s1
	v_mfma_f32_32x32x16_bf16 v[2:17], v[96:99], v[188:191], v[2:17]
	global_load_lds_dwordx4 v[66:67], off
	v_mfma_f32_32x32x16_bf16 v[34:49], v[96:99], v[192:195], v[34:49]
	v_mfma_f32_32x32x16_bf16 v[18:33], v[100:103], v[212:215], v[18:33]
	s_add_i32 m0, s1, 0x400
	v_mfma_f32_32x32x16_bf16 v[50:65], v[100:103], v[216:219], v[50:65]
	global_load_lds_dwordx4 v[70:71], off
	v_mfma_f32_32x32x16_bf16 v[2:17], v[144:147], v[212:215], v[2:17]
	v_mfma_f32_32x32x16_bf16 v[34:49], v[144:147], v[216:219], v[34:49]
	v_mfma_f32_32x32x16_bf16 v[18:33], v[148:151], v[220:223], v[18:33]
	v_mfma_f32_32x32x16_bf16 v[50:65], v[148:151], v[224:227], v[50:65]
	s_add_i32 m0, s1, 0x800
	v_mfma_f32_32x32x16_bf16 v[2:17], v[152:155], v[220:223], v[2:17]
	global_load_lds_dwordx4 v[74:75], off
	v_mfma_f32_32x32x16_bf16 v[34:49], v[152:155], v[224:227], v[34:49]
	v_mfma_f32_32x32x16_bf16 v[18:33], v[180:183], v[228:231], v[18:33]
	s_add_i32 m0, s1, 0xc00
	v_mfma_f32_32x32x16_bf16 v[50:65], v[180:183], v[252:255], v[50:65]
	global_load_lds_dwordx4 v[78:79], off
	v_mfma_f32_32x32x16_bf16 v[2:17], v[184:187], v[228:231], v[2:17]
	v_mfma_f32_32x32x16_bf16 v[34:49], v[184:187], v[252:255], v[34:49]
	s_waitcnt vmcnt(4)
	s_barrier
	ds_read_b128 v[92:95], v84 offset:32768
	ds_read_b128 v[96:99], v84 offset:36864
	ds_read_b128 v[100:103], v86 offset:32768
	ds_read_b128 v[144:147], v86 offset:36864
	ds_read_b128 v[148:151], v88 offset:32768
	ds_read_b128 v[152:155], v88 offset:36864
	ds_read_b128 v[180:183], v90 offset:32768
	ds_read_b128 v[184:187], v90 offset:36864
	s_waitcnt lgkmcnt(0)
	s_barrier
	v_mfma_f32_32x32x16_bf16 v[104:119], v[92:95], v[188:191], v[104:119]
	v_mfma_f32_32x32x16_bf16 v[128:143], v[92:95], v[192:195], v[128:143]
	s_mov_b32 m0, s6
	v_lshl_add_u64 v[82:83], v[66:67], 0, s[26:27]
	v_mfma_f32_32x32x16_bf16 v[196:211], v[96:99], v[188:191], v[196:211]
	global_load_lds_dwordx4 v[82:83], off
	v_lshl_add_u64 v[66:67], v[66:67], 0, s[34:35]
	v_mfma_f32_32x32x16_bf16 v[236:251], v[96:99], v[192:195], v[236:251]
	v_mfma_f32_32x32x16_bf16 v[104:119], v[100:103], v[212:215], v[104:119]
	s_mov_b32 m0, s13
	v_lshl_add_u64 v[82:83], v[70:71], 0, s[26:27]
	v_mfma_f32_32x32x16_bf16 v[128:143], v[100:103], v[216:219], v[128:143]
	global_load_lds_dwordx4 v[82:83], off
	v_lshl_add_u64 v[70:71], v[70:71], 0, s[34:35]
	v_mfma_f32_32x32x16_bf16 v[196:211], v[144:147], v[212:215], v[196:211]
	v_mfma_f32_32x32x16_bf16 v[236:251], v[144:147], v[216:219], v[236:251]
	v_mfma_f32_32x32x16_bf16 v[104:119], v[148:151], v[220:223], v[104:119]
	v_mfma_f32_32x32x16_bf16 v[128:143], v[148:151], v[224:227], v[128:143]
	s_mov_b32 m0, s15
	v_lshl_add_u64 v[82:83], v[74:75], 0, s[26:27]
	v_mfma_f32_32x32x16_bf16 v[196:211], v[152:155], v[220:223], v[196:211]
	global_load_lds_dwordx4 v[82:83], off
	v_lshl_add_u64 v[74:75], v[74:75], 0, s[34:35]
	v_mfma_f32_32x32x16_bf16 v[236:251], v[152:155], v[224:227], v[236:251]
	v_mfma_f32_32x32x16_bf16 v[104:119], v[180:183], v[228:231], v[104:119]
	s_mov_b32 m0, s17
	v_lshl_add_u64 v[82:83], v[78:79], 0, s[26:27]
	v_mfma_f32_32x32x16_bf16 v[128:143], v[180:183], v[252:255], v[128:143]
	global_load_lds_dwordx4 v[82:83], off
	v_lshl_add_u64 v[78:79], v[78:79], 0, s[34:35]
	v_mfma_f32_32x32x16_bf16 v[196:211], v[184:187], v[228:231], v[196:211]
	v_mfma_f32_32x32x16_bf16 v[236:251], v[184:187], v[252:255], v[236:251]
	s_waitcnt vmcnt(4)
	s_barrier
	ds_read_b128 v[92:95], v84 offset:0
	ds_read_b128 v[96:99], v84 offset:4096
	ds_read_b128 v[188:191], v85 offset:32768
	ds_read_b128 v[192:195], v85 offset:36864
	ds_read_b128 v[100:103], v86 offset:0
	ds_read_b128 v[144:147], v86 offset:4096
	ds_read_b128 v[212:215], v87 offset:32768
	ds_read_b128 v[216:219], v87 offset:36864
	ds_read_b128 v[148:151], v88 offset:0
	ds_read_b128 v[152:155], v88 offset:4096
	ds_read_b128 v[220:223], v89 offset:32768
	ds_read_b128 v[224:227], v89 offset:36864
	ds_read_b128 v[180:183], v90 offset:0
	ds_read_b128 v[184:187], v90 offset:4096
	ds_read_b128 v[228:231], v91 offset:32768
	ds_read_b128 v[252:255], v91 offset:36864
	s_waitcnt lgkmcnt(0)
	s_barrier
	v_mfma_f32_32x32x16_bf16 v[18:33], v[92:95], v[188:191], v[18:33]
	v_mfma_f32_32x32x16_bf16 v[50:65], v[92:95], v[192:195], v[50:65]
	v_mfma_f32_32x32x16_bf16 v[2:17], v[96:99], v[188:191], v[2:17]
	v_mfma_f32_32x32x16_bf16 v[34:49], v[96:99], v[192:195], v[34:49]
	v_mfma_f32_32x32x16_bf16 v[18:33], v[100:103], v[212:215], v[18:33]
	v_mfma_f32_32x32x16_bf16 v[50:65], v[100:103], v[216:219], v[50:65]
	v_mfma_f32_32x32x16_bf16 v[2:17], v[144:147], v[212:215], v[2:17]
	v_mfma_f32_32x32x16_bf16 v[34:49], v[144:147], v[216:219], v[34:49]
	v_mfma_f32_32x32x16_bf16 v[18:33], v[148:151], v[220:223], v[18:33]
	v_mfma_f32_32x32x16_bf16 v[50:65], v[148:151], v[224:227], v[50:65]
	v_mfma_f32_32x32x16_bf16 v[2:17], v[152:155], v[220:223], v[2:17]
	v_mfma_f32_32x32x16_bf16 v[34:49], v[152:155], v[224:227], v[34:49]
	v_mfma_f32_32x32x16_bf16 v[18:33], v[180:183], v[228:231], v[18:33]
	v_mfma_f32_32x32x16_bf16 v[50:65], v[180:183], v[252:255], v[50:65]
	v_mfma_f32_32x32x16_bf16 v[2:17], v[184:187], v[228:231], v[2:17]
	v_mfma_f32_32x32x16_bf16 v[34:49], v[184:187], v[252:255], v[34:49]
	s_waitcnt vmcnt(0)
	s_barrier
	ds_read_b128 v[92:95], v84 offset:32768
	ds_read_b128 v[96:99], v84 offset:36864
	ds_read_b128 v[100:103], v86 offset:32768
	ds_read_b128 v[144:147], v86 offset:36864
	ds_read_b128 v[148:151], v88 offset:32768
	ds_read_b128 v[152:155], v88 offset:36864
	ds_read_b128 v[180:183], v90 offset:32768
	ds_read_b128 v[184:187], v90 offset:36864
	s_waitcnt lgkmcnt(0)
	s_barrier
	v_mfma_f32_32x32x16_bf16 v[104:119], v[92:95], v[188:191], v[104:119]
	v_mfma_f32_32x32x16_bf16 v[128:143], v[92:95], v[192:195], v[128:143]
	v_mfma_f32_32x32x16_bf16 v[196:211], v[96:99], v[188:191], v[196:211]
	v_mfma_f32_32x32x16_bf16 v[236:251], v[96:99], v[192:195], v[236:251]
	v_mfma_f32_32x32x16_bf16 v[104:119], v[100:103], v[212:215], v[104:119]
	v_mfma_f32_32x32x16_bf16 v[128:143], v[100:103], v[216:219], v[128:143]
	v_mfma_f32_32x32x16_bf16 v[196:211], v[144:147], v[212:215], v[196:211]
	v_mfma_f32_32x32x16_bf16 v[236:251], v[144:147], v[216:219], v[236:251]
	v_mfma_f32_32x32x16_bf16 v[104:119], v[148:151], v[220:223], v[104:119]
	v_mfma_f32_32x32x16_bf16 v[128:143], v[148:151], v[224:227], v[128:143]
	v_mfma_f32_32x32x16_bf16 v[196:211], v[152:155], v[220:223], v[196:211]
	v_mfma_f32_32x32x16_bf16 v[236:251], v[152:155], v[224:227], v[236:251]
	v_mfma_f32_32x32x16_bf16 v[104:119], v[180:183], v[228:231], v[104:119]
	v_mfma_f32_32x32x16_bf16 v[128:143], v[180:183], v[252:255], v[128:143]
	v_mfma_f32_32x32x16_bf16 v[196:211], v[184:187], v[228:231], v[196:211]
	v_mfma_f32_32x32x16_bf16 v[236:251], v[184:187], v[252:255], v[236:251]
	s_waitcnt vmcnt(0) lgkmcnt(0)
	s_barrier

.Lep_store_strided:
	ds_read_b128 v[180:183], v74 offset:0
	ds_read_b128 v[184:187], v74 offset:1152
	ds_read_b128 v[188:191], v74 offset:2304
	ds_read_b128 v[192:195], v74 offset:3456
	ds_read_b128 v[212:215], v74 offset:4608
	ds_read_b128 v[216:219], v74 offset:5760
	ds_read_b128 v[220:223], v74 offset:6912
	ds_read_b128 v[224:227], v74 offset:8064
	s_waitcnt lgkmcnt(7)
	global_store_dwordx4 v75, v[180:183], s[10:11]
	s_add_u32 s10, s10, s16
	s_addc_u32 s11, s11, 0
	s_waitcnt lgkmcnt(6)
	global_store_dwordx4 v75, v[184:187], s[10:11]
	s_add_u32 s10, s10, s16
	s_addc_u32 s11, s11, 0
	s_waitcnt lgkmcnt(5)
	global_store_dwordx4 v75, v[188:191], s[10:11]
	s_add_u32 s10, s10, s16
	s_addc_u32 s11, s11, 0
	s_waitcnt lgkmcnt(4)
	global_store_dwordx4 v75, v[192:195], s[10:11]
	s_add_u32 s10, s10, s16
	s_addc_u32 s11, s11, 0
	s_waitcnt lgkmcnt(3)
	global_store_dwordx4 v75, v[212:215], s[10:11]
	s_add_u32 s10, s10, s16
	s_addc_u32 s11, s11, 0
	s_waitcnt lgkmcnt(2)
	global_store_dwordx4 v75, v[216:219], s[10:11]
	s_add_u32 s10, s10, s16
	s_addc_u32 s11, s11, 0
	s_waitcnt lgkmcnt(1)
	global_store_dwordx4 v75, v[220:223], s[10:11]
	s_add_u32 s10, s10, s16
	s_addc_u32 s11, s11, 0
	s_waitcnt lgkmcnt(0)
	global_store_dwordx4 v75, v[224:227], s[10:11]
	s_branch .LBB0_173
.LBB0_587:
	s_waitcnt vmcnt(0)
	s_barrier
	s_mov_b64 s[0:1], exec
	v_readlane_b32 s4, v234, 0
	v_readlane_b32 s5, v234, 1
	v_readlane_b32 s18, v232, 33
	s_and_b64 s[4:5], s[0:1], s[4:5]
	v_readlane_b32 s19, v232, 34
	s_mov_b64 exec, s[4:5]
	s_cbranch_execz .LBB0_635
	s_waitcnt vmcnt(0) expcnt(0) lgkmcnt(0)
	ds_read_b32 v3, v158
	ds_read_b32 v2, v159
	v_readlane_b32 s12, v232, 35
	v_readlane_b32 s14, v232, 37
	v_readlane_b32 s13, v232, 36
	s_waitcnt lgkmcnt(1)
	v_cmp_ne_u32_e32 vcc, 0, v3
	v_readlane_b32 s15, v232, 38
	s_cbranch_vccnz .LBB0_603
	v_readlane_b32 s6, v234, 18
	v_readlane_b32 s7, v234, 19
	s_load_dwordx2 s[4:5], s[6:7], 0x4
	s_mov_b32 s11, 1
	s_waitcnt lgkmcnt(0)
	s_mul_i32 s10, s4, s60
	s_mul_i32 s10, s10, s5
	s_branch .LBB0_591
